# stagger waves 4-7 by half a tile-step in both attention loops (mid barrier, V stage moved to second half)
# speedup vs baseline: 1.0025x; 1.0025x over previous
; template <int DQK, bool MOBA>
; __device__ __forceinline__ void attn_unit(const Args& A, int b, int h, int qb, lptr lds) {
;     ...
;         __syncthreads();
;     }
;     lrow += __shfl_xor(lrow, 32);
.LBB0_755:
	s_cmp_ge_u32 s71, 0x80
	s_cbranch_scc1 .Lmoba_exit_b
	s_barrier

; __device__ __forceinline__ float bf2f(unsigned short v) { return __uint_as_float(((unsigned)v) << 16); }
; template <int DQK, bool MOBA>
; __device__ __forceinline__ void attn_unit(const Args& A, int b, int h, int qb, lptr lds) {
;     ...
;         float qss = 0.f;
; #pragma unroll
;         for (int s = 0; s < NS; ++s)
; #pragma unroll
;             for (int e = 0; e < 8; ++e) { const float f = bf2f((unsigned short)qf[s][e]); qss += f * f; }
;         qss += __shfl_xor(qss, 32);
;         float gmx = fmaxf(fabsf(A.gk_n[lane]), fabsf(A.gk_n[lane + 64]));
;         float grx = (DQK == 192) ? fabsf(A.gk_r[lane]) : 0.f;
;         float bmx = (MOBA && lane < 32) ? fabsf(A.relb[lane * 8 + h]) * 1.4426950408889634f : 0.f;
; #pragma unroll
;         for (int o_ = 1; o_ < 64; o_ <<= 1) { gmx = fmaxf(gmx, __shfl_xor(gmx, o_)); grx = fmaxf(grx, __shfl_xor(grx, o_)); bmx = fmaxf(bmx, __shfl_xor(bmx, o_)); }
;         negm = -(sqrtf(qss * (128.0f * gmx * gmx + 64.0f * grx * grx)) * 1.01f + bmx + 0.01f);
;     }
;     const int NT = 4 * (own + 1);
;     u32x4 kr0, kr1, kr2, vr0, vr1; int pkr = 0;
;     kr2 = (u32x4){0u, 0u, 0u, 0u};
;     ...
;     f32x16 o[4];
; #pragma unroll
;     for (int d = 0; d < 4; ++d)
; #pragma unroll
;         for (int r = 0; r < 16; ++r) o[d][r] = 0.f;
;     float lrow = 0.f;
;     ATT_LOAD(0); ATT_WRITE(0);
;     if (NT > 1) ATT_LOAD(1);
;     __syncthreads();
;     ...
;         if (t + 1 < NT) { ATT_WRITE(buf ^ 1); if (t + 2 < NT) ATT_LOAD(t + 2); }
.LBB0_779:
	s_or_b64 exec, exec, s[0:1]
	s_waitcnt lgkmcnt(5)
	v_max_f32_e32 v1, v21, v21
	v_max_f32_e32 v2, v19, v19
	v_max_f32_e32 v1, v2, v1
	v_mul_f32_e32 v3, 0x43000000, v1
	v_add_f32_e32 v0, v16, v17
	v_fma_f32 v1, v1, v3, 0
	v_mul_f32_e32 v0, v0, v1
	v_mul_f32_e32 v1, 0x4f800000, v0
	v_cmp_gt_f32_e32 vcc, s35, v0
	s_waitcnt lgkmcnt(4)
	v_max_f32_e32 v2, v20, v20
	v_max_f32_e32 v3, v18, v18
	v_cndmask_b32_e32 v0, v0, v1, vcc
	v_sqrt_f32_e32 v1, v0
	v_max_f32_e32 v2, v3, v2
	s_lshl_b32 s18, s18, 2
	s_add_i32 s19, s18, 4
	v_add_u32_e32 v3, -1, v1
	v_fma_f32 v4, -v3, v1, v0
	v_cmp_ge_f32_e64 s[0:1], 0, v4
	v_add_u32_e32 v4, 1, v1
	v_lshlrev_b32_e32 v176, 2, v82
	v_cndmask_b32_e64 v3, v1, v3, s[0:1]
	v_fma_f32 v1, -v4, v1, v0
	v_cmp_lt_f32_e64 s[0:1], 0, v1
	v_mov_b32_e32 v48, v181
	v_mov_b32_e32 v49, v181
	v_cndmask_b32_e64 v1, v3, v4, s[0:1]
	v_mul_f32_e32 v3, 0x37800000, v1
	v_cndmask_b32_e32 v1, v1, v3, vcc
	v_cmp_class_f32_e32 vcc, v0, v205
	s_add_i32 s0, 0, 0x12800
	v_lshlrev_b32_e32 v3, 3, v162
	v_cndmask_b32_e32 v0, v1, v0, vcc
	v_mul_u32_u24_e32 v1, 0x110, v83
	v_fmac_f32_e32 v2, 0x3f8147ae, v0
	v_add3_u32 v179, 0, v1, v36
	v_lshrrev_b32_e32 v1, 2, v162
	v_add_f32_e32 v0, 0x3c23d70a, v2
	v_and_or_b32 v1, v1, 3, v176
	v_lshlrev_b32_e32 v2, 1, v162
	s_add_u32 s20, s95, s4
	v_mad_u32_u24 v1, v1, s12, 0
	v_and_b32_e32 v2, 32, v2
	v_and_b32_e32 v3, 24, v3
	s_addc_u32 s21, s8, s5
	v_mul_lo_u32 v174, v22, s12
	v_add3_u32 v183, v1, v2, v3
	v_xor_b32_e32 v64, 0x80000000, v0
	v_bfi_b32 v115, s14, v37, v37
	s_add_u32 s22, s9, s4
	v_add_u32_e32 v185, s0, v36
	v_mov_b32_e32 v50, v181
	v_mov_b32_e32 v51, v181
	v_mov_b32_e32 v52, v181
	v_mov_b32_e32 v53, v181
	v_mov_b32_e32 v54, v181
	v_mov_b32_e32 v55, v181
	v_mov_b32_e32 v56, v181
	v_mov_b32_e32 v57, v181
	v_mov_b32_e32 v58, v181
	v_mov_b32_e32 v59, v181
	v_mov_b32_e32 v60, v181
	v_mov_b32_e32 v61, v181
	v_mov_b32_e32 v62, v181
	v_mov_b32_e32 v63, v181
	v_mov_b64_e32 v[32:33], v[48:49]
	v_mov_b64_e32 v[16:17], v[48:49]
	v_mov_b64_e32 v[0:1], v[48:49]
	v_add_u32_e32 v163, 0x2200, v167
	v_add_u32_e32 v175, 0x2800, v174
	s_mov_b32 s13, 0
	s_mov_b32 s15, 2
	v_or_b32_e32 v177, s71, v83
	v_lshl_add_u32 v178, v162, 2, s0
	v_mov_b32_e32 v65, v64
	v_mov_b32_e32 v66, v64
	v_mov_b32_e32 v67, v64
	v_mov_b32_e32 v68, v64
	v_mov_b32_e32 v69, v64
	v_mov_b32_e32 v70, v64
	v_mov_b32_e32 v71, v64
	v_mov_b32_e32 v72, v64
	v_mov_b32_e32 v73, v64
	v_mov_b32_e32 v74, v64
	v_mov_b32_e32 v75, v64
	v_mov_b32_e32 v76, v64
	v_mov_b32_e32 v77, v64
	v_mov_b32_e32 v78, v64
	v_mov_b32_e32 v79, v64
	v_bfi_b32 v119, s14, v84, v84
	v_bfi_b32 v123, s14, v80, v80
	v_bfi_b32 v127, s14, v81, v81
	v_bfi_b32 v131, s14, v85, v85
	v_bfi_b32 v135, s14, v86, v86
	v_bfi_b32 v139, s14, v87, v87
	v_bfi_b32 v143, s14, v88, v88
	s_addc_u32 s23, s10, s5
	s_addk_i32 s17, 0x100
	v_mov_b32_e32 v184, 0
	v_mov_b64_e32 v[34:35], v[50:51]
	v_mov_b64_e32 v[36:37], v[52:53]
	v_mov_b64_e32 v[38:39], v[54:55]
	v_mov_b64_e32 v[40:41], v[56:57]
	v_mov_b64_e32 v[42:43], v[58:59]
	v_mov_b64_e32 v[44:45], v[60:61]
	v_mov_b64_e32 v[46:47], v[62:63]
	v_mov_b64_e32 v[18:19], v[50:51]
	v_mov_b64_e32 v[20:21], v[52:53]
	v_mov_b64_e32 v[22:23], v[54:55]
	v_mov_b64_e32 v[24:25], v[56:57]
	v_mov_b64_e32 v[26:27], v[58:59]
	v_mov_b64_e32 v[28:29], v[60:61]
	v_mov_b64_e32 v[30:31], v[62:63]
	v_mov_b64_e32 v[2:3], v[50:51]
	v_mov_b64_e32 v[4:5], v[52:53]
	v_mov_b64_e32 v[6:7], v[54:55]
	v_mov_b64_e32 v[8:9], v[56:57]
	v_mov_b64_e32 v[10:11], v[58:59]
	v_mov_b64_e32 v[12:13], v[60:61]
	v_mov_b64_e32 v[14:15], v[62:63]
	s_waitcnt lgkmcnt(0)
	s_barrier
	s_cmp_lt_u32 s71, 0x80
	s_cbranch_scc1 .LBB0_782
	s_barrier
	s_branch .LBB0_782
.LBB0_780:
	s_waitcnt lgkmcnt(0)
	s_barrier
	s_add_i32 s0, s15, -1
	s_cmp_ge_u32 s0, s19
	s_cbranch_scc1 .Lmoba_mid_done_a
	s_xor_b32 s4, s24, 1
	s_mul_i32 s1, s4, 0x5000
	s_cmp_ge_u32 s15, s19
	s_cbranch_scc1 .Lmoba_w0_a
	s_waitcnt vmcnt(2)
	s_branch .Lmoba_w1_a

.Lmoba_w1_a:
	v_add3_u32 v227, s1, v174, v166
	ds_write_b128 v227, v[152:155] offset:34816
	v_add3_u32 v227, s1, v175, v166
	ds_write_b128 v227, v[156:159] offset:34816
	s_and_saveexec_b64 s[0:1], s[40:41]
	v_lshl_add_u32 v227, s4, 8, v178
	ds_write_b32 v227, v173
	s_or_b64 exec, exec, s[0:1]
	s_cmp_ge_u32 s15, s19
	s_cbranch_scc1 .Lmoba_mid_done_a
	s_add_i32 s0, s18, s15
	s_add_i32 s1, s15, -4
	s_add_i32 s6, s15, -2
	s_cmp_lt_u32 s6, 2
	s_cselect_b32 s0, s0, s1
	s_lshl_b32 s4, s0, 6
	s_add_i32 s4, s4, s70
	s_mul_i32 s7, s4, 0x1800
	s_mul_hi_i32 s5, s4, 0x1800
	s_add_u32 s0, s22, s7
	s_addc_u32 s1, s23, s5
	v_lshl_add_u64 v[228:229], s[0:1], 0, v[164:165]
	v_lshl_add_u64 v[230:231], s[0:1], 0, v[168:169]
	v_lshl_add_u64 v[228:229], v[228:229], 0, v[180:181]
	v_lshl_add_u64 v[230:231], v[230:231], 0, v[180:181]
	global_load_dwordx4 v[152:155], v[228:229], off
	global_load_dwordx4 v[156:159], v[230:231], off
	s_and_saveexec_b64 s[0:1], s[40:41]
	s_cbranch_execz .Lmoba_pos_a
	v_add_u32_e32 v228, s4, v162
	v_ashrrev_i32_e32 v229, 31, v228
	v_lshl_add_u64 v[228:229], v[228:229], 2, s[54:55]
	global_load_dword v173, v[228:229], off
.Lmoba_pos_a:
	s_or_b64 exec, exec, s[0:1]
; __device__ __forceinline__ unsigned cvt_pk_bf16(float lo, float hi) { f32x2 v = {lo, hi}; bf16x2_t b = __builtin_convertvector(v, bf16x2_t); return __builtin_bit_cast(unsigned, b); }
; #define LAS __attribute__((address_space(3)))
; #define MFMA32(a, b, c) __builtin_amdgcn_mfma_f32_32x32x16_bf16((a), (b), (c), 0, 0, 0)
; template <int DQK, bool MOBA>
; __device__ __forceinline__ void attn_unit(const Args& A, int b, int h, int qb, lptr lds) {
;     ...
;             float ls = 0.f;
; #pragma unroll
;             for (int r = 0; r < 16; ++r) { s0[r] = __builtin_amdgcn_exp2f(s0[r]); s1[r] = __builtin_amdgcn_exp2f(s1[r]); ls += s0[r] + s1[r]; }
;             lrow += ls;
;             bf16x8 pb[4];
; #pragma unroll
;             for (int g = 0; g < 2; ++g) {
;                 u32x4 w0, w1;
;                 w0.x = cvt_pk_bf16(s0[8 * g + 0], s0[8 * g + 1]); w0.y = cvt_pk_bf16(s0[8 * g + 2], s0[8 * g + 3]); w0.z = cvt_pk_bf16(s0[8 * g + 4], s0[8 * g + 5]); w0.w = cvt_pk_bf16(s0[8 * g + 6], s0[8 * g + 7]);
;                 w1.x = cvt_pk_bf16(s1[8 * g + 0], s1[8 * g + 1]); w1.y = cvt_pk_bf16(s1[8 * g + 2], s1[8 * g + 3]); w1.z = cvt_pk_bf16(s1[8 * g + 4], s1[8 * g + 5]); w1.w = cvt_pk_bf16(s1[8 * g + 6], s1[8 * g + 7]);
;                 pb[g] = __builtin_bit_cast(bf16x8, w0); pb[2 + g] = __builtin_bit_cast(bf16x8, w1);
;             }
;             lptr vb = lds + L::OFF_V + buf * L::VBUF + (4 * hi + ((lane & 15) >> 2)) * VROW + ((lane >> 4) & 1) * 32 + (lane & 3) * 8;
; #pragma unroll
;             for (int d = 0; d < 4; ++d) {
;                 s16x4 lo[4], hi4[4];
; #pragma unroll
;                 for (int g = 0; g < 4; ++g) {
;                     lo[g] = __builtin_bit_cast(s16x4, __builtin_amdgcn_ds_read_tr16_b64_v4i16((LAS s16x4*)(vb + (16 * g) * VROW + d * 64)));
;                     hi4[g] = __builtin_bit_cast(s16x4, __builtin_amdgcn_ds_read_tr16_b64_v4i16((LAS s16x4*)(vb + (16 * g + 8) * VROW + d * 64)));
;                 }
;                 __builtin_amdgcn_sched_barrier(0);
; #pragma unroll
;                 for (int g = 0; g < 4; ++g) {
;                     const bf16x8 av = __builtin_shufflevector(lo[g], hi4[g], 0, 1, 2, 3, 4, 5, 6, 7);
;                     o[d] = MFMA32(av, pb[g], o[d]);
;                 }
;             }
.Lmoba_mid_done_a:
	v_exp_f32_e32 v188, v106
	v_exp_f32_e32 v189, v110
	v_exp_f32_e32 v190, v107
	v_exp_f32_e32 v191, v111
	v_exp_f32_e32 v192, v104
	v_exp_f32_e32 v193, v108
	v_exp_f32_e32 v194, v105
	v_exp_f32_e32 v195, v109
	v_add_f32_e32 v106, v188, v189
	v_add_f32_e32 v106, 0, v106
	v_add_f32_e32 v107, v190, v191
	v_add_f32_e32 v106, v107, v106
	v_add_f32_e32 v104, v192, v193
	v_add_f32_e32 v104, v104, v106
	v_add_f32_e32 v105, v194, v195
	v_add_f32_e32 v108, v105, v104
	v_exp_f32_e32 v107, v98
	v_exp_f32_e32 v105, v102
	v_exp_f32_e32 v106, v99
	v_exp_f32_e32 v104, v103
	v_exp_f32_e32 v103, v100
	v_exp_f32_e32 v102, v101
	v_exp_f32_e32 v109, v88
	v_pk_add_f32 v[98:99], v[106:107], v[104:105]
	v_exp_f32_e32 v111, v80
	v_add_f32_e32 v99, v99, v108
	v_add_f32_e32 v108, v98, v99
	v_exp_f32_e32 v99, v94
	v_exp_f32_e32 v98, v97
	v_exp_f32_e32 v97, v92
	v_exp_f32_e32 v110, v81
	v_exp_f32_e32 v187, v86
	v_pk_add_f32 v[100:101], v[98:99], v[102:103]
	v_exp_f32_e32 v186, v87
	v_add_f32_e32 v94, v101, v108
	v_add_f32_e32 v108, v100, v94
	v_exp_f32_e32 v101, v96
	v_exp_f32_e32 v96, v91
	v_exp_f32_e32 v100, v95
	v_pk_mov_b32 v[86:87], v[104:105], v[104:105] op_sel:[1,0]
	s_mulk_i32 s24, 0x5000
	v_cvt_pk_bf16_f32 v86, v86, v87
	v_pk_add_f32 v[94:95], v[96:97], v[100:101]
	v_pk_add_f32 v[80:81], v[110:111], v[186:187]
	v_add_f32_e32 v91, v95, v108
	v_add_f32_e32 v92, v94, v91
	v_exp_f32_e32 v91, v84
	v_exp_f32_e32 v95, v90
	v_exp_f32_e32 v90, v85
	v_exp_f32_e32 v94, v93
	v_exp_f32_e32 v93, v82
	v_exp_f32_e32 v108, v89
	v_pk_mov_b32 v[88:89], v[102:103], v[102:103] op_sel:[1,0]
	v_pk_add_f32 v[84:85], v[90:91], v[94:95]
	v_cvt_pk_bf16_f32 v87, v88, v89
	v_add_f32_e32 v85, v85, v92
	v_exp_f32_e32 v92, v83
	v_pk_mov_b32 v[88:89], v[96:97], v[96:97] op_sel:[1,0]
	v_pk_mov_b32 v[90:91], v[90:91], v[90:91] op_sel:[1,0]
	v_add_f32_e32 v84, v84, v85
	v_pk_add_f32 v[82:83], v[92:93], v[108:109]
	v_cvt_pk_bf16_f32 v88, v88, v89
	v_cvt_pk_bf16_f32 v89, v90, v91
	v_pk_mov_b32 v[90:91], v[92:93], v[92:93] op_sel:[1,0]
	v_pk_mov_b32 v[92:93], v[110:111], v[110:111] op_sel:[1,0]
	v_add_f32_e32 v83, v83, v84
	v_cvt_pk_bf16_f32 v90, v90, v91
	v_cvt_pk_bf16_f32 v91, v92, v93
	v_pk_mov_b32 v[92:93], v[100:101], v[100:101] op_sel:[1,0]
	v_pk_mov_b32 v[94:95], v[94:95], v[94:95] op_sel:[1,0]
	v_add_f32_e32 v82, v82, v83
	v_cvt_pk_bf16_f32 v92, v92, v93
	v_cvt_pk_bf16_f32 v93, v94, v95
	v_pk_mov_b32 v[94:95], v[108:109], v[108:109] op_sel:[1,0]
	v_pk_mov_b32 v[96:97], v[186:187], v[186:187] op_sel:[1,0]
	v_add_u32_e32 v186, s24, v183
	v_add_f32_e32 v81, v81, v82
	v_pk_mov_b32 v[82:83], v[106:107], v[106:107] op_sel:[1,0]
	v_pk_mov_b32 v[84:85], v[98:99], v[98:99] op_sel:[1,0]
	v_cvt_pk_bf16_f32 v94, v94, v95
	v_cvt_pk_bf16_f32 v95, v96, v97
	ds_read_b64_tr_b16 v[96:97], v186 offset:34816
	ds_read_b64_tr_b16 v[98:99], v186 offset:37376
	ds_read_b64_tr_b16 v[100:101], v186 offset:39936
	ds_read_b64_tr_b16 v[102:103], v186 offset:42496
	ds_read_b64_tr_b16 v[104:105], v186 offset:45056
	ds_read_b64_tr_b16 v[106:107], v186 offset:47616
	ds_read_b64_tr_b16 v[108:109], v186 offset:50176
	ds_read_b64_tr_b16 v[110:111], v186 offset:52736
	v_add_f32_e32 v196, v80, v81
	v_cvt_pk_bf16_f32 v80, v188, v190
	v_cvt_pk_bf16_f32 v81, v192, v194
	v_cvt_pk_bf16_f32 v82, v82, v83
	v_cvt_pk_bf16_f32 v83, v84, v85
	v_cvt_pk_bf16_f32 v84, v189, v191
	v_cvt_pk_bf16_f32 v85, v193, v195
	s_waitcnt lgkmcnt(6)
	v_mfma_f32_32x32x16_bf16 v[48:63], v[96:99], v[80:83], v[48:63]
	s_waitcnt lgkmcnt(4)
	v_mfma_f32_32x32x16_bf16 v[48:63], v[100:103], v[88:91], v[48:63]
	s_waitcnt lgkmcnt(2)
	v_mfma_f32_32x32x16_bf16 v[48:63], v[104:107], v[84:87], v[48:63]
	s_waitcnt lgkmcnt(0)
	v_mfma_f32_32x32x16_bf16 v[48:63], v[108:111], v[92:95], v[48:63]
	ds_read_b64_tr_b16 v[96:97], v186 offset:34880
	ds_read_b64_tr_b16 v[98:99], v186 offset:37440
	ds_read_b64_tr_b16 v[100:101], v186 offset:40000
	ds_read_b64_tr_b16 v[102:103], v186 offset:42560
	ds_read_b64_tr_b16 v[104:105], v186 offset:45120
	ds_read_b64_tr_b16 v[106:107], v186 offset:47680
	ds_read_b64_tr_b16 v[108:109], v186 offset:50240
	ds_read_b64_tr_b16 v[110:111], v186 offset:52800
	s_waitcnt lgkmcnt(6)
	v_mfma_f32_32x32x16_bf16 v[32:47], v[96:99], v[80:83], v[32:47]
	s_waitcnt lgkmcnt(4)
	v_mfma_f32_32x32x16_bf16 v[32:47], v[100:103], v[88:91], v[32:47]
	s_waitcnt lgkmcnt(2)
	v_mfma_f32_32x32x16_bf16 v[32:47], v[104:107], v[84:87], v[32:47]
	s_waitcnt lgkmcnt(0)
	v_mfma_f32_32x32x16_bf16 v[32:47], v[108:111], v[92:95], v[32:47]
	ds_read_b64_tr_b16 v[96:97], v186 offset:34944
	ds_read_b64_tr_b16 v[98:99], v186 offset:37504
	ds_read_b64_tr_b16 v[100:101], v186 offset:40064
	ds_read_b64_tr_b16 v[102:103], v186 offset:42624
	ds_read_b64_tr_b16 v[104:105], v186 offset:45184
	ds_read_b64_tr_b16 v[106:107], v186 offset:47744
	ds_read_b64_tr_b16 v[108:109], v186 offset:50304
	ds_read_b64_tr_b16 v[110:111], v186 offset:52864
	s_waitcnt lgkmcnt(6)
	v_mfma_f32_32x32x16_bf16 v[16:31], v[96:99], v[80:83], v[16:31]
	s_waitcnt lgkmcnt(4)
	v_mfma_f32_32x32x16_bf16 v[16:31], v[100:103], v[88:91], v[16:31]
	s_waitcnt lgkmcnt(2)
	v_mfma_f32_32x32x16_bf16 v[16:31], v[104:107], v[84:87], v[16:31]
	s_waitcnt lgkmcnt(0)
	v_mfma_f32_32x32x16_bf16 v[16:31], v[108:111], v[92:95], v[16:31]
	ds_read_b64_tr_b16 v[96:97], v186 offset:35008
	ds_read_b64_tr_b16 v[98:99], v186 offset:37568
	ds_read_b64_tr_b16 v[100:101], v186 offset:40128
	ds_read_b64_tr_b16 v[102:103], v186 offset:42688
	ds_read_b64_tr_b16 v[104:105], v186 offset:45248
	ds_read_b64_tr_b16 v[106:107], v186 offset:47808
	ds_read_b64_tr_b16 v[108:109], v186 offset:50368
	ds_read_b64_tr_b16 v[110:111], v186 offset:52928
	s_waitcnt lgkmcnt(6)
	v_mfma_f32_32x32x16_bf16 v[0:15], v[96:99], v[80:83], v[0:15]
	v_add_f32_e32 v184, v184, v196
	s_waitcnt lgkmcnt(4)
	v_mfma_f32_32x32x16_bf16 v[0:15], v[100:103], v[88:91], v[0:15]
	s_waitcnt lgkmcnt(2)
	v_mfma_f32_32x32x16_bf16 v[0:15], v[104:107], v[84:87], v[0:15]
	s_waitcnt lgkmcnt(0)
	v_mfma_f32_32x32x16_bf16 v[0:15], v[108:111], v[92:95], v[0:15]

; template <int DQK, bool MOBA>
; __device__ __forceinline__ void attn_unit(const Args& A, int b, int h, int qb, lptr lds) {
;     ...
;         if (t + 1 < NT) { ATT_WRITE(buf ^ 1); if (t + 2 < NT) ATT_LOAD(t + 2); }
.LBB0_782:
	s_add_i32 s6, s15, -2
	s_and_b32 s24, s6, 1
	s_add_i32 s0, s15, -1
	s_cmp_ge_u32 s0, s19
	s_cbranch_scc1 .LBB0_789
	s_xor_b32 s4, s24, 1
	s_mul_i32 s0, s4, 0x4400
	v_add3_u32 v80, s0, v167, v166
	s_waitcnt vmcnt(2)
	ds_write_b128 v80, v[144:147]
	v_add3_u32 v80, s0, v163, v166
	ds_write_b128 v80, v[148:151]
	s_cmp_ge_u32 s15, s19
	s_cbranch_scc1 .LBB0_789
	s_add_i32 s0, s18, s15
	s_add_i32 s1, s15, -4
	s_cmp_lt_u32 s6, 2
	s_cselect_b32 s0, s0, s1
	s_lshl_b32 s4, s0, 6
	s_add_i32 s4, s4, s70
	s_mul_i32 s7, s4, 0x1800
	s_mul_hi_i32 s5, s4, 0x1800
	s_add_u32 s0, s20, s7
	s_addc_u32 s1, s21, s5
	v_lshl_add_u64 v[80:81], s[0:1], 0, v[164:165]
	v_lshl_add_u64 v[82:83], s[0:1], 0, v[168:169]
	v_lshl_add_u64 v[80:81], v[80:81], 0, v[180:181]
	v_lshl_add_u64 v[82:83], v[82:83], 0, v[180:181]
	global_load_dwordx4 v[144:147], v[80:81], off
	global_load_dwordx4 v[148:151], v[82:83], off

; template <int DQK, bool MOBA>
; __device__ __forceinline__ void attn_unit(const Args& A, int b, int h, int qb, lptr lds) {
;     ...
;         if (t + 1 < NT) { ATT_WRITE(buf ^ 1); if (t + 2 < NT) ATT_LOAD(t + 2); }
.Lmoba_pos_b:
	s_or_b64 exec, exec, s[0:1]
.Lmoba_mid_done_b:
	s_branch .LBB0_781
.LBB0_796:
	s_mov_b64 s[4:5], 0

; __device__ __forceinline__ unsigned cvt_pk_bf16(float lo, float hi) { f32x2 v = {lo, hi}; bf16x2_t b = __builtin_convertvector(v, bf16x2_t); return __builtin_bit_cast(unsigned, b); }
; #define LAS __attribute__((address_space(3)))
; #define MFMA32(a, b, c) __builtin_amdgcn_mfma_f32_32x32x16_bf16((a), (b), (c), 0, 0, 0)
; template <int DQK, bool MOBA>
; __device__ __forceinline__ void attn_unit(const Args& A, int b, int h, int qb, lptr lds) {
;     ...
;             float ls = 0.f;
; #pragma unroll
;             for (int r = 0; r < 16; ++r) { s0[r] = __builtin_amdgcn_exp2f(s0[r]); s1[r] = __builtin_amdgcn_exp2f(s1[r]); ls += s0[r] + s1[r]; }
;             lrow += ls;
;             bf16x8 pb[4];
; #pragma unroll
;             for (int g = 0; g < 2; ++g) {
;                 u32x4 w0, w1;
;                 w0.x = cvt_pk_bf16(s0[8 * g + 0], s0[8 * g + 1]); w0.y = cvt_pk_bf16(s0[8 * g + 2], s0[8 * g + 3]); w0.z = cvt_pk_bf16(s0[8 * g + 4], s0[8 * g + 5]); w0.w = cvt_pk_bf16(s0[8 * g + 6], s0[8 * g + 7]);
;                 w1.x = cvt_pk_bf16(s1[8 * g + 0], s1[8 * g + 1]); w1.y = cvt_pk_bf16(s1[8 * g + 2], s1[8 * g + 3]); w1.z = cvt_pk_bf16(s1[8 * g + 4], s1[8 * g + 5]); w1.w = cvt_pk_bf16(s1[8 * g + 6], s1[8 * g + 7]);
;                 pb[g] = __builtin_bit_cast(bf16x8, w0); pb[2 + g] = __builtin_bit_cast(bf16x8, w1);
;             }
;             lptr vb = lds + L::OFF_V + buf * L::VBUF + (4 * hi + ((lane & 15) >> 2)) * VROW + ((lane >> 4) & 1) * 32 + (lane & 3) * 8;
; #pragma unroll
;             for (int d = 0; d < 4; ++d) {
;                 s16x4 lo[4], hi4[4];
; #pragma unroll
;                 for (int g = 0; g < 4; ++g) {
;                     lo[g] = __builtin_bit_cast(s16x4, __builtin_amdgcn_ds_read_tr16_b64_v4i16((LAS s16x4*)(vb + (16 * g) * VROW + d * 64)));
;                     hi4[g] = __builtin_bit_cast(s16x4, __builtin_amdgcn_ds_read_tr16_b64_v4i16((LAS s16x4*)(vb + (16 * g + 8) * VROW + d * 64)));
;                 }
;                 __builtin_amdgcn_sched_barrier(0);
; #pragma unroll
;                 for (int g = 0; g < 4; ++g) {
;                     const bf16x8 av = __builtin_shufflevector(lo[g], hi4[g], 0, 1, 2, 3, 4, 5, 6, 7);
;                     o[d] = MFMA32(av, pb[g], o[d]);
;                 }
;             }
.LBB0_802:
	s_waitcnt lgkmcnt(0)
	s_barrier
	s_nop 7
	v_exp_f32_e32 v98, v80
	s_nop 0
	v_exp_f32_e32 v99, v64
	v_exp_f32_e32 v100, v81
	v_exp_f32_e32 v101, v65
	v_exp_f32_e32 v102, v82
	v_exp_f32_e32 v103, v66
	v_exp_f32_e32 v104, v83
	v_exp_f32_e32 v105, v67
	v_add_f32_e32 v64, v98, v99
	v_exp_f32_e32 v67, v84
	v_exp_f32_e32 v81, v68
	v_exp_f32_e32 v66, v85
	v_exp_f32_e32 v80, v69
	v_add_f32_e32 v64, 0, v64
	v_add_f32_e32 v65, v100, v101
	v_add_f32_e32 v64, v65, v64
	v_add_f32_e32 v65, v102, v103
	v_add_f32_e32 v64, v65, v64
	v_add_f32_e32 v65, v104, v105
	v_add_f32_e32 v82, v65, v64
	v_pk_add_f32 v[64:65], v[66:67], v[80:81]
	v_exp_f32_e32 v69, v86
	v_add_f32_e32 v65, v65, v82
	v_exp_f32_e32 v83, v70
	v_exp_f32_e32 v68, v87
	v_exp_f32_e32 v82, v71
	v_add_f32_e32 v84, v64, v65
	v_exp_f32_e32 v85, v88
	v_exp_f32_e32 v87, v72
	v_pk_add_f32 v[64:65], v[68:69], v[82:83]
	v_exp_f32_e32 v86, v73
	v_add_f32_e32 v65, v65, v84
	v_exp_f32_e32 v84, v89
	v_exp_f32_e32 v89, v90
	v_exp_f32_e32 v97, v74
	v_exp_f32_e32 v88, v91
	v_exp_f32_e32 v96, v75
	v_add_f32_e32 v70, v64, v65
	v_pk_add_f32 v[64:65], v[84:85], v[86:87]
	v_exp_f32_e32 v75, v92
	v_exp_f32_e32 v91, v76
	v_exp_f32_e32 v74, v93
	v_exp_f32_e32 v90, v77
	v_add_f32_e32 v65, v65, v70
	v_add_f32_e32 v70, v64, v65
	v_pk_add_f32 v[64:65], v[88:89], v[96:97]
	v_exp_f32_e32 v77, v94
	v_exp_f32_e32 v93, v78
	v_exp_f32_e32 v76, v95
	v_exp_f32_e32 v92, v79
	v_add_f32_e32 v65, v65, v70
	v_add_f32_e32 v70, v64, v65
	v_pk_add_f32 v[64:65], v[74:75], v[90:91]
	v_pk_mov_b32 v[72:73], v[82:83], v[82:83] op_sel:[1,0]
	v_add_f32_e32 v65, v65, v70
	v_add_f32_e32 v70, v64, v65
	v_pk_add_f32 v[64:65], v[76:77], v[92:93]
	v_pk_mov_b32 v[78:79], v[88:89], v[88:89] op_sel:[1,0]
	v_add_f32_e32 v65, v65, v70
	v_pk_mov_b32 v[70:71], v[80:81], v[80:81] op_sel:[1,0]
	v_pk_mov_b32 v[74:75], v[74:75], v[74:75] op_sel:[1,0]
	v_cvt_pk_bf16_f32 v70, v70, v71
	v_cvt_pk_bf16_f32 v71, v72, v73
	v_pk_mov_b32 v[72:73], v[84:85], v[84:85] op_sel:[1,0]
	v_pk_mov_b32 v[76:77], v[76:77], v[76:77] op_sel:[1,0]
	v_cvt_pk_bf16_f32 v72, v72, v73
	v_cvt_pk_bf16_f32 v73, v78, v79
	v_cvt_pk_bf16_f32 v74, v74, v75
	v_cvt_pk_bf16_f32 v75, v76, v77
	v_pk_mov_b32 v[76:77], v[86:87], v[86:87] op_sel:[1,0]
	v_pk_mov_b32 v[78:79], v[96:97], v[96:97] op_sel:[1,0]
	s_mulk_i32 s4, 0x5000
	v_cvt_pk_bf16_f32 v76, v76, v77
	v_cvt_pk_bf16_f32 v77, v78, v79
	v_pk_mov_b32 v[78:79], v[90:91], v[90:91] op_sel:[1,0]
	v_pk_mov_b32 v[80:81], v[92:93], v[92:93] op_sel:[1,0]
	v_add_u32_e32 v96, s4, v198
	v_cvt_pk_bf16_f32 v78, v78, v79
	v_cvt_pk_bf16_f32 v79, v80, v81
	v_add_u32_e32 v97, 0xc800, v96
	ds_read_b64_tr_b16 v[80:81], v96 offset:51200
	ds_read_b64_tr_b16 v[82:83], v96 offset:53760
	ds_read_b64_tr_b16 v[84:85], v96 offset:56320
	ds_read_b64_tr_b16 v[86:87], v96 offset:58880
	ds_read_b64_tr_b16 v[88:89], v96 offset:61440
	ds_read_b64_tr_b16 v[90:91], v96 offset:64000
	ds_read_b64_tr_b16 v[92:93], v97 offset:15360
	ds_read_b64_tr_b16 v[94:95], v97 offset:17920
	v_pk_mov_b32 v[66:67], v[66:67], v[66:67] op_sel:[1,0]
	v_pk_mov_b32 v[68:69], v[68:69], v[68:69] op_sel:[1,0]
	v_add_f32_e32 v106, v64, v65
	v_cvt_pk_bf16_f32 v64, v98, v100
	v_cvt_pk_bf16_f32 v65, v102, v104
	v_cvt_pk_bf16_f32 v66, v66, v67
	v_cvt_pk_bf16_f32 v67, v68, v69
	v_cvt_pk_bf16_f32 v68, v99, v101
	v_cvt_pk_bf16_f32 v69, v103, v105
	s_waitcnt lgkmcnt(6)
	v_mfma_f32_32x32x16_bf16 v[48:63], v[80:83], v[64:67], v[48:63]
	s_waitcnt lgkmcnt(4)
	v_mfma_f32_32x32x16_bf16 v[48:63], v[84:87], v[72:75], v[48:63]
	s_waitcnt lgkmcnt(2)
	v_mfma_f32_32x32x16_bf16 v[48:63], v[88:91], v[68:71], v[48:63]
	s_waitcnt lgkmcnt(0)
	v_mfma_f32_32x32x16_bf16 v[48:63], v[92:95], v[76:79], v[48:63]
	ds_read_b64_tr_b16 v[80:81], v96 offset:51264
	ds_read_b64_tr_b16 v[82:83], v96 offset:53824
	ds_read_b64_tr_b16 v[84:85], v96 offset:56384
	ds_read_b64_tr_b16 v[86:87], v96 offset:58944
	ds_read_b64_tr_b16 v[88:89], v96 offset:61504
	ds_read_b64_tr_b16 v[90:91], v96 offset:64064
	ds_read_b64_tr_b16 v[92:93], v97 offset:15424
	ds_read_b64_tr_b16 v[94:95], v97 offset:17984
	s_waitcnt lgkmcnt(6)
	v_mfma_f32_32x32x16_bf16 v[32:47], v[80:83], v[64:67], v[32:47]
	s_waitcnt lgkmcnt(4)
	v_mfma_f32_32x32x16_bf16 v[32:47], v[84:87], v[72:75], v[32:47]
	s_waitcnt lgkmcnt(2)
	v_mfma_f32_32x32x16_bf16 v[32:47], v[88:91], v[68:71], v[32:47]
	s_waitcnt lgkmcnt(0)
	v_mfma_f32_32x32x16_bf16 v[32:47], v[92:95], v[76:79], v[32:47]
	ds_read_b64_tr_b16 v[80:81], v96 offset:51328
	ds_read_b64_tr_b16 v[82:83], v96 offset:53888
	ds_read_b64_tr_b16 v[84:85], v96 offset:56448
	ds_read_b64_tr_b16 v[86:87], v96 offset:59008
	ds_read_b64_tr_b16 v[88:89], v96 offset:61568
	ds_read_b64_tr_b16 v[90:91], v96 offset:64128
	ds_read_b64_tr_b16 v[92:93], v97 offset:15488
	ds_read_b64_tr_b16 v[94:95], v97 offset:18048
	s_waitcnt lgkmcnt(6)
	v_mfma_f32_32x32x16_bf16 v[16:31], v[80:83], v[64:67], v[16:31]
	s_waitcnt lgkmcnt(4)
	v_mfma_f32_32x32x16_bf16 v[16:31], v[84:87], v[72:75], v[16:31]
	s_waitcnt lgkmcnt(2)
	v_mfma_f32_32x32x16_bf16 v[16:31], v[88:91], v[68:71], v[16:31]
	s_waitcnt lgkmcnt(0)
	v_mfma_f32_32x32x16_bf16 v[16:31], v[92:95], v[76:79], v[16:31]
	ds_read_b64_tr_b16 v[80:81], v96 offset:51392
	ds_read_b64_tr_b16 v[82:83], v96 offset:53952
	ds_read_b64_tr_b16 v[84:85], v96 offset:56512
	ds_read_b64_tr_b16 v[86:87], v96 offset:59072
	ds_read_b64_tr_b16 v[88:89], v96 offset:61632
	ds_read_b64_tr_b16 v[90:91], v96 offset:64192
	ds_read_b64_tr_b16 v[92:93], v97 offset:15552
	ds_read_b64_tr_b16 v[94:95], v97 offset:18112
	s_waitcnt lgkmcnt(6)
	v_mfma_f32_32x32x16_bf16 v[0:15], v[80:83], v[64:67], v[0:15]
	v_add_f32_e32 v187, v187, v106
	s_waitcnt lgkmcnt(4)
	v_mfma_f32_32x32x16_bf16 v[0:15], v[84:87], v[72:75], v[0:15]
	s_waitcnt lgkmcnt(2)
	v_mfma_f32_32x32x16_bf16 v[0:15], v[88:91], v[68:71], v[0:15]
	s_waitcnt lgkmcnt(0)
	v_mfma_f32_32x32x16_bf16 v[0:15], v[92:95], v[76:79], v[0:15]
; __device__ __forceinline__ unsigned cvt_pk_bf16(float lo, float hi) { f32x2 v = {lo, hi}; bf16x2_t b = __builtin_convertvector(v, bf16x2_t); return __builtin_bit_cast(unsigned, b); }
; template <int DQK, bool MOBA>
; __device__ __forceinline__ void attn_unit(const Args& A, int b, int h, int qb, lptr lds) {
;     ...
;         __syncthreads();
;     }
;     lrow += __shfl_xor(lrow, 32);
;     const float inv = 1.0f / lrow;
;     bf16* op = A.O + (size_t)qrow * 1024 + h * 128 + 4 * hi;
; #pragma unroll
;     for (int d = 0; d < 4; ++d)
; #pragma unroll
;         for (int a = 0; a < 4; ++a) {
;             u32x2 w; w.x = cvt_pk_bf16(o[d][4 * a] * inv, o[d][4 * a + 1] * inv); w.y = cvt_pk_bf16(o[d][4 * a + 2] * inv, o[d][4 * a + 3] * inv);
;             *(u32x2*)(op + 32 * d + 8 * a) = w;
;         }
.LBB0_803:
	ds_bpermute_b32 v64, v196, v187
	v_lshlrev_b32_e32 v180, 1, v183
	s_waitcnt lgkmcnt(0)
	s_barrier
	v_readfirstlane_b32 s0, v202
	s_nop 3
	s_cmp_ge_u32 s0, 0x100
	s_cbranch_scc1 .Lmla_exit_b
	s_barrier
.Lmla_exit_b:
	v_add_f32_e32 v64, v187, v64
	v_div_scale_f32 v65, s[0:1], v64, v64, 1.0
	v_rcp_f32_e32 v66, v65
	v_div_scale_f32 v67, vcc, 1.0, v64, 1.0
	v_readlane_b32 s0, v253, 58
	v_fma_f32 v68, -v65, v66, 1.0
	v_fmac_f32_e32 v66, v68, v66
	v_mul_f32_e32 v68, v67, v66
	v_fma_f32 v69, -v65, v68, v67
	v_fmac_f32_e32 v68, v69, v66
	v_fma_f32 v65, -v65, v68, v67
	v_div_fmas_f32 v65, v65, v66, v68
	v_lshlrev_b64 v[66:67], 11, v[184:185]
	v_readlane_b32 s1, v253, 59
	v_div_fixup_f32 v64, v65, v64, 1.0
	v_pk_mul_f32 v[48:49], v[48:49], v[64:65] op_sel_hi:[1,0]
	v_lshl_add_u64 v[66:67], s[0:1], 0, v[66:67]
	v_lshl_add_u64 v[66:67], s[42:43], 1, v[66:67]
	v_pk_mul_f32 v[50:51], v[50:51], v[64:65] op_sel_hi:[1,0]
	v_pk_mul_f32 v[32:33], v[32:33], v[64:65] op_sel_hi:[1,0]
	v_pk_mul_f32 v[34:35], v[34:35], v[64:65] op_sel_hi:[1,0]
	v_pk_mul_f32 v[16:17], v[16:17], v[64:65] op_sel_hi:[1,0]
	v_pk_mul_f32 v[18:19], v[18:19], v[64:65] op_sel_hi:[1,0]
	v_pk_mul_f32 v[0:1], v[0:1], v[64:65] op_sel_hi:[1,0]
	v_pk_mul_f32 v[2:3], v[2:3], v[64:65] op_sel_hi:[1,0]
	v_lshl_add_u64 v[66:67], v[66:67], 0, v[180:181]
	v_cvt_pk_bf16_f32 v48, v48, v49
	v_cvt_pk_bf16_f32 v49, v50, v51
	v_cvt_pk_bf16_f32 v32, v32, v33
	v_cvt_pk_bf16_f32 v33, v34, v35
	v_cvt_pk_bf16_f32 v16, v16, v17
	v_cvt_pk_bf16_f32 v17, v18, v19
	v_cvt_pk_bf16_f32 v0, v0, v1
	v_cvt_pk_bf16_f32 v1, v2, v3
	global_store_dwordx2 v[66:67], v[48:49], off
	v_pk_mul_f32 v[48:49], v[52:53], v[64:65] op_sel_hi:[1,0]
	v_pk_mul_f32 v[50:51], v[54:55], v[64:65] op_sel_hi:[1,0]
	global_store_dwordx2 v[66:67], v[32:33], off offset:64
	v_pk_mul_f32 v[32:33], v[36:37], v[64:65] op_sel_hi:[1,0]
	v_pk_mul_f32 v[34:35], v[38:39], v[64:65] op_sel_hi:[1,0]
	global_store_dwordx2 v[66:67], v[16:17], off offset:128
	v_pk_mul_f32 v[16:17], v[20:21], v[64:65] op_sel_hi:[1,0]
	v_pk_mul_f32 v[18:19], v[22:23], v[64:65] op_sel_hi:[1,0]
	global_store_dwordx2 v[66:67], v[0:1], off offset:192
	v_pk_mul_f32 v[0:1], v[4:5], v[64:65] op_sel_hi:[1,0]
	v_pk_mul_f32 v[2:3], v[6:7], v[64:65] op_sel_hi:[1,0]
	v_cvt_pk_bf16_f32 v48, v48, v49
	v_cvt_pk_bf16_f32 v49, v50, v51
	v_cvt_pk_bf16_f32 v32, v32, v33
	v_cvt_pk_bf16_f32 v33, v34, v35
	v_cvt_pk_bf16_f32 v16, v16, v17
	v_cvt_pk_bf16_f32 v17, v18, v19
	v_cvt_pk_bf16_f32 v0, v0, v1
	v_cvt_pk_bf16_f32 v1, v2, v3
	global_store_dwordx2 v[66:67], v[48:49], off offset:16
	v_pk_mul_f32 v[48:49], v[56:57], v[64:65] op_sel_hi:[1,0]
	v_pk_mul_f32 v[50:51], v[58:59], v[64:65] op_sel_hi:[1,0]
	global_store_dwordx2 v[66:67], v[32:33], off offset:80
	v_pk_mul_f32 v[32:33], v[40:41], v[64:65] op_sel_hi:[1,0]
	v_pk_mul_f32 v[34:35], v[42:43], v[64:65] op_sel_hi:[1,0]
	global_store_dwordx2 v[66:67], v[16:17], off offset:144
	v_pk_mul_f32 v[16:17], v[24:25], v[64:65] op_sel_hi:[1,0]
	v_pk_mul_f32 v[18:19], v[26:27], v[64:65] op_sel_hi:[1,0]
	global_store_dwordx2 v[66:67], v[0:1], off offset:208
	v_pk_mul_f32 v[0:1], v[8:9], v[64:65] op_sel_hi:[1,0]
	v_pk_mul_f32 v[2:3], v[10:11], v[64:65] op_sel_hi:[1,0]
	v_cvt_pk_bf16_f32 v48, v48, v49
	v_cvt_pk_bf16_f32 v49, v50, v51
	v_cvt_pk_bf16_f32 v32, v32, v33
	v_cvt_pk_bf16_f32 v33, v34, v35
	v_cvt_pk_bf16_f32 v16, v16, v17
	v_cvt_pk_bf16_f32 v17, v18, v19
	v_cvt_pk_bf16_f32 v0, v0, v1
	v_cvt_pk_bf16_f32 v1, v2, v3
	global_store_dwordx2 v[66:67], v[48:49], off offset:32
	v_pk_mul_f32 v[48:49], v[60:61], v[64:65] op_sel_hi:[1,0]
	v_pk_mul_f32 v[50:51], v[62:63], v[64:65] op_sel_hi:[1,0]
	global_store_dwordx2 v[66:67], v[32:33], off offset:96
	v_pk_mul_f32 v[32:33], v[44:45], v[64:65] op_sel_hi:[1,0]
	v_pk_mul_f32 v[34:35], v[46:47], v[64:65] op_sel_hi:[1,0]
	global_store_dwordx2 v[66:67], v[16:17], off offset:160
	v_pk_mul_f32 v[16:17], v[28:29], v[64:65] op_sel_hi:[1,0]
	v_pk_mul_f32 v[18:19], v[30:31], v[64:65] op_sel_hi:[1,0]
	global_store_dwordx2 v[66:67], v[0:1], off offset:224
	v_pk_mul_f32 v[0:1], v[12:13], v[64:65] op_sel_hi:[1,0]
	v_pk_mul_f32 v[2:3], v[14:15], v[64:65] op_sel_hi:[1,0]
	s_add_i32 s21, s21, 1
	v_cvt_pk_bf16_f32 v48, v48, v49
	v_cvt_pk_bf16_f32 v49, v50, v51
	v_cvt_pk_bf16_f32 v32, v32, v33
	v_cvt_pk_bf16_f32 v33, v34, v35
	v_cvt_pk_bf16_f32 v16, v16, v17
	v_cvt_pk_bf16_f32 v17, v18, v19
	v_cvt_pk_bf16_f32 v0, v0, v1
	v_cvt_pk_bf16_f32 v1, v2, v3
	s_cmp_eq_u32 s21, 4
	global_store_dwordx2 v[66:67], v[48:49], off offset:48
	global_store_dwordx2 v[66:67], v[32:33], off offset:112
	global_store_dwordx2 v[66:67], v[16:17], off offset:176
	global_store_dwordx2 v[66:67], v[0:1], off offset:240
	s_cbranch_scc1 .LBB0_800

; __device__ __forceinline__ float bf2f(unsigned short v) { return __uint_as_float(((unsigned)v) << 16); }
; template <int DQK, bool MOBA>
; __device__ __forceinline__ void attn_unit(const Args& A, int b, int h, int qb, lptr lds) {
;     ...
;     int tid_o = threadIdx.x; asm volatile("" : "+v"(tid_o));
;     const int tid = tid_o, lane = tid & 63, r32 = lane & 31, hi = lane >> 5;
;     const int wid = __builtin_amdgcn_readfirstlane(tid >> 6);
;     const int tb = b * SEQ, q0 = qb * 256, own = qb, bh = b * NH + h;
;     const int qrow = tb + q0 + wid * 32 + r32;
;     const int qrel = wid * 32 + r32;
;     __syncthreads();
;     bf16x8 qf[NS];
;     {
;         const bf16* qp = A.Q + (size_t)qrow * A.q_pitch + h * DQK + 8 * hi;
; #pragma unroll
;         for (int s = 0; s < NS; ++s) qf[s] = *(const bf16x8*)(qp + 16 * s);
;     }
;     {
;         float ssn = 0.f;
; #pragma unroll
;         for (int s = 0; s < 8; ++s)
; #pragma unroll
;             for (int e = 0; e < 8; ++e) { const float f = bf2f((unsigned short)qf[s][e]); ssn += f * f; }
;         ssn += __shfl_xor(ssn, 32);
;         const float scn = __builtin_amdgcn_rsqf(ssn * (1.0f / 128.0f) + 1e-6f) * A.qscale;
; #pragma unroll
;         for (int s = 0; s < 8; ++s) {
;             const f32x4 g0 = *(const f32x4*)(A.gq_n + 16 * s + 8 * hi), g1 = *(const f32x4*)(A.gq_n + 16 * s + 8 * hi + 4);
.LBB0_809:
	s_lshl_b32 s0, s21, 2
	s_add_i32 s0, s0, s19
	s_ashr_i32 s1, s0, 31
	s_lshr_b32 s1, s1, 29
	s_add_i32 s1, s0, s1
	v_mov_b32_e32 v106, v202
	s_and_b32 s4, s1, -8
	s_lshl_b32 s1, s1, 8
	v_readfirstlane_b32 s5, v106
	s_and_b32 s24, s1, 0xfffff800
	s_lshl_b32 s13, s22, 8
	s_ashr_i32 s15, s5, 1
	s_sub_i32 s0, s0, s4
	s_add_i32 s4, s13, s24
	s_and_b32 s23, s15, 0xffffffe0
	v_and_b32_e32 v108, 31, v106
	s_add_i32 s1, s23, s4
	v_or_b32_e32 v184, s1, v108
	v_mov_b64_e32 v[0:1], s[88:89]
	v_mad_i64_i32 v[0:1], s[6:7], v184, s11, v[0:1]
	s_mul_i32 s6, s0, 0xc0
	v_bfe_u32 v107, v106, 5, 1
	s_ashr_i32 s7, s6, 31
	v_lshl_add_u64 v[0:1], s[6:7], 1, v[0:1]
	v_lshlrev_b32_e32 v180, 4, v107
	v_lshl_add_u64 v[82:83], v[0:1], 0, v[180:181]
	v_and_b32_e32 v76, 32, v106
	s_barrier
	global_load_dwordx4 v[84:87], v[82:83], off offset:224
	global_load_dwordx4 v[90:93], v[82:83], off offset:192
	global_load_dwordx4 v[98:101], v[82:83], off offset:160
	global_load_dwordx4 v[68:71], v[82:83], off offset:128
	global_load_dwordx4 v[60:63], v[82:83], off offset:96
	global_load_dwordx4 v[56:59], v[82:83], off offset:64
	global_load_dwordx4 v[48:51], v76, s[28:29] offset:16
	global_load_dwordx4 v[52:55], v76, s[28:29]
	global_load_dwordx4 v[40:43], v76, s[28:29] offset:80
	global_load_dwordx4 v[44:47], v76, s[28:29] offset:64
	global_load_dwordx4 v[32:35], v76, s[28:29] offset:144
	global_load_dwordx4 v[36:39], v76, s[28:29] offset:128
	global_load_dwordx4 v[24:27], v76, s[28:29] offset:208
	global_load_dwordx4 v[28:31], v76, s[28:29] offset:192
	global_load_dwordx4 v[64:67], v[82:83], off
	global_load_dwordx4 v[112:115], v[82:83], off offset:32
	global_load_dwordx4 v[16:19], v76, s[28:29] offset:272
	global_load_dwordx4 v[20:23], v76, s[28:29] offset:256
	global_load_dwordx4 v[8:11], v76, s[28:29] offset:336
	global_load_dwordx4 v[12:15], v76, s[28:29] offset:320
	v_and_b32_e32 v1, 64, v206
	v_xor_b32_e32 v0, 32, v206
	v_add_u32_e32 v109, 64, v1
	v_cmp_lt_i32_e32 vcc, v0, v109
	v_ashrrev_i32_e32 v185, 31, v184
	v_mov_b32_e32 v77, v181
	v_cndmask_b32_e32 v0, v206, v0, vcc
	v_lshlrev_b32_e32 v196, 2, v0
	global_load_dwordx4 v[0:3], v[82:83], off offset:256
	global_load_dwordx4 v[4:7], v[82:83], off offset:288
	v_and_b32_e32 v110, 63, v106
	s_lshl_b32 s25, s22, 2
	s_ashr_i32 s5, s4, 31
	s_add_i32 s26, s25, 4
	s_lshl_b64 s[44:45], s[4:5], 11
	s_add_u32 s1, s90, s44
	s_addc_u32 s5, s91, s45
	s_lshl_b32 s42, s0, 7
	s_ashr_i32 s43, s42, 31
	s_lshl_b64 s[6:7], s[42:43], 1
	s_add_u32 s0, s1, s6
	s_addc_u32 s1, s5, s7
	s_mov_b32 s5, 2
	s_mov_b32 s27, 0
	s_waitcnt vmcnt(21)
	v_and_b32_e32 v73, 0xffff0000, v87
	s_waitcnt vmcnt(7)
	v_and_b32_e32 v201, 0xffff0000, v64
	v_lshlrev_b32_e32 v200, 16, v64
	v_and_b32_e32 v195, 0xffff0000, v65
	v_lshlrev_b32_e32 v194, 16, v65
	v_pk_mul_f32 v[64:65], v[200:201], v[200:201]
	v_pk_mul_f32 v[198:199], v[194:195], v[194:195]
	v_add_f32_e32 v64, v64, v65
	v_and_b32_e32 v193, 0xffff0000, v66
	v_lshlrev_b32_e32 v192, 16, v66
	v_add_f32_e32 v64, v198, v64
	v_and_b32_e32 v189, 0xffff0000, v67
	v_lshlrev_b32_e32 v188, 16, v67
	v_pk_mul_f32 v[66:67], v[192:193], v[192:193]
	v_add_f32_e32 v64, v199, v64
	v_add_f32_e32 v64, v66, v64
	v_pk_mul_f32 v[190:191], v[188:189], v[188:189]
	v_add_f32_e32 v64, v67, v64
	s_waitcnt vmcnt(6)
	v_and_b32_e32 v187, 0xffff0000, v112
	v_lshlrev_b32_e32 v186, 16, v112
	v_add_f32_e32 v64, v190, v64
	v_and_b32_e32 v177, 0xffff0000, v113
	v_lshlrev_b32_e32 v176, 16, v113
	v_pk_mul_f32 v[112:113], v[186:187], v[186:187]
	v_add_f32_e32 v64, v191, v64
	v_add_f32_e32 v64, v112, v64
	v_pk_mul_f32 v[178:179], v[176:177], v[176:177]
	v_add_f32_e32 v64, v113, v64
	v_and_b32_e32 v175, 0xffff0000, v114
	v_lshlrev_b32_e32 v174, 16, v114
	v_add_f32_e32 v64, v178, v64
	v_and_b32_e32 v171, 0xffff0000, v115
	v_lshlrev_b32_e32 v170, 16, v115
	v_pk_mul_f32 v[114:115], v[174:175], v[174:175]
	v_add_f32_e32 v64, v179, v64
	v_add_f32_e32 v64, v114, v64
	v_pk_mul_f32 v[172:173], v[170:171], v[170:171]
	v_add_f32_e32 v64, v115, v64
	v_and_b32_e32 v169, 0xffff0000, v56
	v_lshlrev_b32_e32 v168, 16, v56
	v_add_f32_e32 v64, v172, v64
	v_and_b32_e32 v165, 0xffff0000, v57
	v_lshlrev_b32_e32 v164, 16, v57
	v_pk_mul_f32 v[56:57], v[168:169], v[168:169]
	v_add_f32_e32 v64, v173, v64
	v_add_f32_e32 v56, v56, v64
	v_pk_mul_f32 v[166:167], v[164:165], v[164:165]
	v_add_f32_e32 v56, v57, v56
	v_and_b32_e32 v163, 0xffff0000, v58
	v_lshlrev_b32_e32 v162, 16, v58
	v_add_f32_e32 v56, v166, v56
	v_and_b32_e32 v159, 0xffff0000, v59
	v_lshlrev_b32_e32 v158, 16, v59
	v_pk_mul_f32 v[58:59], v[162:163], v[162:163]
	v_add_f32_e32 v56, v167, v56
	v_add_f32_e32 v56, v58, v56
	v_pk_mul_f32 v[160:161], v[158:159], v[158:159]
	v_add_f32_e32 v56, v59, v56
	v_and_b32_e32 v157, 0xffff0000, v60
	v_lshlrev_b32_e32 v156, 16, v60
	v_add_f32_e32 v56, v160, v56
	v_and_b32_e32 v155, 0xffff0000, v61
	v_lshlrev_b32_e32 v154, 16, v61
	v_pk_mul_f32 v[60:61], v[156:157], v[156:157]
	v_add_f32_e32 v56, v161, v56
	v_add_f32_e32 v56, v60, v56
	v_pk_mul_f32 v[148:149], v[154:155], v[154:155]
	v_add_f32_e32 v56, v61, v56
	v_and_b32_e32 v153, 0xffff0000, v62
	v_lshlrev_b32_e32 v152, 16, v62
	v_add_f32_e32 v56, v148, v56
	v_and_b32_e32 v151, 0xffff0000, v63
	v_lshlrev_b32_e32 v150, 16, v63
	v_pk_mul_f32 v[62:63], v[152:153], v[152:153]
	v_add_f32_e32 v56, v149, v56
	v_add_f32_e32 v56, v62, v56
	v_pk_mul_f32 v[146:147], v[150:151], v[150:151]
	v_add_f32_e32 v56, v63, v56
	v_and_b32_e32 v105, 0xffff0000, v68
	v_lshlrev_b32_e32 v104, 16, v68
	v_add_f32_e32 v56, v146, v56
	v_and_b32_e32 v103, 0xffff0000, v69
	v_lshlrev_b32_e32 v102, 16, v69
	v_pk_mul_f32 v[68:69], v[104:105], v[104:105]
; __device__ __forceinline__ unsigned cvt_pk_bf16(float lo, float hi) { f32x2 v = {lo, hi}; bf16x2_t b = __builtin_convertvector(v, bf16x2_t); return __builtin_bit_cast(unsigned, b); }
; __device__ __forceinline__ float bf2f(unsigned short v) { return __uint_as_float(((unsigned)v) << 16); }
; template <int DQK, bool MOBA>
; __device__ __forceinline__ void attn_unit(const Args& A, int b, int h, int qb, lptr lds) {
;     ...
;         float ssn = 0.f;
; #pragma unroll
;         for (int s = 0; s < 8; ++s)
; #pragma unroll
;             for (int e = 0; e < 8; ++e) { const float f = bf2f((unsigned short)qf[s][e]); ssn += f * f; }
;         ssn += __shfl_xor(ssn, 32);
;         const float scn = __builtin_amdgcn_rsqf(ssn * (1.0f / 128.0f) + 1e-6f) * A.qscale;
; #pragma unroll
;         for (int s = 0; s < 8; ++s) {
;             const f32x4 g0 = *(const f32x4*)(A.gq_n + 16 * s + 8 * hi), g1 = *(const f32x4*)(A.gq_n + 16 * s + 8 * hi + 4);
;             u32x4 w;
;             w.x = cvt_pk_bf16(bf2f((unsigned short)qf[s][0]) * scn * g0[0], bf2f((unsigned short)qf[s][1]) * scn * g0[1]);
;             w.y = cvt_pk_bf16(bf2f((unsigned short)qf[s][2]) * scn * g0[2], bf2f((unsigned short)qf[s][3]) * scn * g0[3]);
;             w.z = cvt_pk_bf16(bf2f((unsigned short)qf[s][4]) * scn * g1[0], bf2f((unsigned short)qf[s][5]) * scn * g1[1]);
;             w.w = cvt_pk_bf16(bf2f((unsigned short)qf[s][6]) * scn * g1[2], bf2f((unsigned short)qf[s][7]) * scn * g1[3]);
;             qf[s] = __builtin_bit_cast(bf16x8, w);
;         }
	v_add_f32_e32 v56, v147, v56
	v_add_f32_e32 v56, v68, v56
	v_pk_mul_f32 v[144:145], v[102:103], v[102:103]
	v_add_f32_e32 v56, v69, v56
	v_lshlrev_b32_e32 v72, 16, v87
	v_and_b32_e32 v75, 0xffff0000, v86
	v_lshlrev_b32_e32 v74, 16, v86
	v_and_b32_e32 v79, 0xffff0000, v85
	v_lshlrev_b32_e32 v78, 16, v85
	v_and_b32_e32 v81, 0xffff0000, v84
	v_lshlrev_b32_e32 v80, 16, v84
	v_and_b32_e32 v85, 0xffff0000, v93
	v_lshlrev_b32_e32 v84, 16, v93
	v_and_b32_e32 v87, 0xffff0000, v92
	v_lshlrev_b32_e32 v86, 16, v92
	v_and_b32_e32 v93, 0xffff0000, v101
	v_lshlrev_b32_e32 v92, 16, v101
	v_and_b32_e32 v95, 0xffff0000, v100
	v_lshlrev_b32_e32 v94, 16, v100
	v_and_b32_e32 v101, 0xffff0000, v71
	v_lshlrev_b32_e32 v100, 16, v71
	v_and_b32_e32 v71, 0xffff0000, v70
	v_lshlrev_b32_e32 v70, 16, v70
	v_add_f32_e32 v56, v144, v56
	v_pk_mul_f32 v[142:143], v[70:71], v[70:71]
	v_add_f32_e32 v56, v145, v56
	v_add_f32_e32 v56, v142, v56
	v_pk_mul_f32 v[140:141], v[100:101], v[100:101]
	v_add_f32_e32 v56, v143, v56
	v_and_b32_e32 v97, 0xffff0000, v99
	v_lshlrev_b32_e32 v96, 16, v99
	v_and_b32_e32 v99, 0xffff0000, v98
	v_lshlrev_b32_e32 v98, 16, v98
	v_add_f32_e32 v56, v140, v56
	v_pk_mul_f32 v[138:139], v[98:99], v[98:99]
	v_add_f32_e32 v56, v141, v56
	v_add_f32_e32 v56, v138, v56
	v_pk_mul_f32 v[136:137], v[96:97], v[96:97]
	v_add_f32_e32 v56, v139, v56
	v_add_f32_e32 v56, v136, v56
	v_pk_mul_f32 v[134:135], v[94:95], v[94:95]
	v_add_f32_e32 v56, v137, v56
	v_add_f32_e32 v56, v134, v56
	v_pk_mul_f32 v[132:133], v[92:93], v[92:93]
	v_add_f32_e32 v56, v135, v56
	v_and_b32_e32 v89, 0xffff0000, v91
	v_lshlrev_b32_e32 v88, 16, v91
	v_and_b32_e32 v91, 0xffff0000, v90
	v_lshlrev_b32_e32 v90, 16, v90
	v_add_f32_e32 v56, v132, v56
	v_pk_mul_f32 v[130:131], v[90:91], v[90:91]
	v_add_f32_e32 v56, v133, v56
	v_add_f32_e32 v56, v130, v56
	v_pk_mul_f32 v[128:129], v[88:89], v[88:89]
	v_add_f32_e32 v56, v131, v56
	v_add_f32_e32 v56, v128, v56
	v_pk_mul_f32 v[126:127], v[86:87], v[86:87]
	v_add_f32_e32 v56, v129, v56
	v_add_f32_e32 v56, v126, v56
	v_pk_mul_f32 v[124:125], v[84:85], v[84:85]
	v_add_f32_e32 v56, v127, v56
	v_add_f32_e32 v56, v124, v56
	v_pk_mul_f32 v[122:123], v[80:81], v[80:81]
	v_add_f32_e32 v56, v125, v56
	v_add_f32_e32 v56, v122, v56
	v_pk_mul_f32 v[120:121], v[78:79], v[78:79]
	v_add_f32_e32 v56, v123, v56
	v_add_f32_e32 v56, v120, v56
	v_pk_mul_f32 v[118:119], v[74:75], v[74:75]
	v_add_f32_e32 v56, v121, v56
	v_add_f32_e32 v56, v118, v56
	v_pk_mul_f32 v[116:117], v[72:73], v[72:73]
	v_add_f32_e32 v56, v119, v56
	v_add_f32_e32 v56, v116, v56
	v_add_f32_e32 v56, v117, v56
	global_load_dwordx4 v[60:63], v[82:83], off offset:320
	global_load_dwordx4 v[64:67], v[82:83], off offset:352
	global_load_dwordx4 v[138:141], v76, s[28:29] offset:400
	global_load_dwordx4 v[142:145], v76, s[28:29] offset:384
	ds_bpermute_b32 v57, v196, v56
	v_ashrrev_i32_e32 v199, 3, v106
	s_waitcnt lgkmcnt(0)
	v_add_f32_e32 v56, v56, v57
	v_fmamk_f32 v56, v56, 0x3c000000, v204
	v_rsq_f32_e32 v68, v56
	global_load_dwordx4 v[56:59], v76, s[28:29] offset:464
	global_load_dwordx4 v[146:149], v76, s[28:29] offset:448
	v_mul_f32_e32 v68, 0x3dd53b94, v68
	v_pk_mul_f32 v[82:83], v[68:69], v[200:201] op_sel_hi:[0,1]
	v_pk_mul_f32 v[52:53], v[52:53], v[82:83]
	s_nop 0
	v_cvt_pk_bf16_f32 v112, v52, v53
	v_pk_mul_f32 v[52:53], v[68:69], v[194:195] op_sel_hi:[0,1]
	v_pk_mul_f32 v[52:53], v[54:55], v[52:53]
	s_nop 0
	v_cvt_pk_bf16_f32 v113, v52, v53
	v_pk_mul_f32 v[52:53], v[68:69], v[192:193] op_sel_hi:[0,1]
	v_pk_mul_f32 v[48:49], v[48:49], v[52:53]
	s_nop 0
	v_cvt_pk_bf16_f32 v114, v48, v49
	v_pk_mul_f32 v[48:49], v[68:69], v[188:189] op_sel_hi:[0,1]
	v_pk_mul_f32 v[48:49], v[50:51], v[48:49]
	v_mov_b32_e32 v189, v181
	v_cvt_pk_bf16_f32 v115, v48, v49
	v_pk_mul_f32 v[48:49], v[68:69], v[186:187] op_sel_hi:[0,1]
	v_pk_mul_f32 v[44:45], v[44:45], v[48:49]
	v_mov_b32_e32 v187, v181
	v_cvt_pk_bf16_f32 v116, v44, v45
	v_pk_mul_f32 v[44:45], v[68:69], v[176:177] op_sel_hi:[0,1]
	v_pk_mul_f32 v[44:45], v[46:47], v[44:45]
	s_nop 0
	v_cvt_pk_bf16_f32 v117, v44, v45
	v_pk_mul_f32 v[44:45], v[68:69], v[174:175] op_sel_hi:[0,1]
	v_pk_mul_f32 v[40:41], v[40:41], v[44:45]
	s_nop 0
	v_cvt_pk_bf16_f32 v118, v40, v41
	v_pk_mul_f32 v[40:41], v[68:69], v[170:171] op_sel_hi:[0,1]
	v_pk_mul_f32 v[40:41], v[42:43], v[40:41]
	s_nop 0
	v_cvt_pk_bf16_f32 v119, v40, v41
	v_pk_mul_f32 v[40:41], v[68:69], v[168:169] op_sel_hi:[0,1]
	v_pk_mul_f32 v[36:37], v[36:37], v[40:41]
	s_waitcnt vmcnt(5)
; __device__ __forceinline__ float bf2f(unsigned short v) { return __uint_as_float(((unsigned)v) << 16); }
; template <int DQK, bool MOBA>
; __device__ __forceinline__ void attn_unit(const Args& A, int b, int h, int qb, lptr lds) {
;     ...
;         if (DQK == 192) {
;             float ssr = 0.f;
; #pragma unroll
;             for (int s = 8; s < NS; ++s)
; #pragma unroll
;                 for (int e = 0; e < 8; ++e) { const float f = bf2f((unsigned short)qf[s][e]); ssr += f * f; }
;             ssr += __shfl_xor(ssr, 32);
;             const float scr = __builtin_amdgcn_rsqf(ssr * (1.0f / 64.0f) + 1e-6f);
; #pragma unroll
;             for (int sp = 0; sp < 2; ++sp) {
;                 const int i0 = 16 * sp + 8 * hi;
;                 float o1[8], o2[8];
;                 const f32x4 ga0 = *(const f32x4*)(A.gq_r + i0), ga1 = *(const f32x4*)(A.gq_r + i0 + 4), gb0 = *(const f32x4*)(A.gq_r + 32 + i0), gb1 = *(const f32x4*)(A.gq_r + 32 + i0 + 4);
;                 const f32x4 cc0 = *(const f32x4*)(A.cosT + (size_t)qrow * 32 + i0), cc1 = *(const f32x4*)(A.cosT + (size_t)qrow * 32 + i0 + 4);
;                 const f32x4 ss0 = *(const f32x4*)(A.sinT + (size_t)qrow * 32 + i0), ss1 = *(const f32x4*)(A.sinT + (size_t)qrow * 32 + i0 + 4);
	v_and_b32_e32 v169, 0xffff0000, v61
	v_cvt_pk_bf16_f32 v120, v36, v37
	v_pk_mul_f32 v[36:37], v[68:69], v[164:165] op_sel_hi:[0,1]
	v_pk_mul_f32 v[36:37], v[38:39], v[36:37]
	v_and_b32_e32 v165, 0xffff0000, v1
	v_cvt_pk_bf16_f32 v121, v36, v37
	v_pk_mul_f32 v[36:37], v[68:69], v[162:163] op_sel_hi:[0,1]
	v_pk_mul_f32 v[32:33], v[32:33], v[36:37]
	v_lshlrev_b32_e32 v164, 16, v1
	v_cvt_pk_bf16_f32 v122, v32, v33
	v_pk_mul_f32 v[32:33], v[68:69], v[158:159] op_sel_hi:[0,1]
	v_pk_mul_f32 v[32:33], v[34:35], v[32:33]
	v_and_b32_e32 v1, 0xffff0000, v0
	v_cvt_pk_bf16_f32 v123, v32, v33
	v_pk_mul_f32 v[32:33], v[68:69], v[156:157] op_sel_hi:[0,1]
	v_pk_mul_f32 v[28:29], v[28:29], v[32:33]
	v_lshlrev_b32_e32 v0, 16, v0
	v_cvt_pk_bf16_f32 v124, v28, v29
	v_pk_mul_f32 v[28:29], v[68:69], v[154:155] op_sel_hi:[0,1]
	v_pk_mul_f32 v[28:29], v[30:31], v[28:29]
	v_pk_mul_f32 v[172:173], v[0:1], v[0:1]
	v_cvt_pk_bf16_f32 v125, v28, v29
	v_pk_mul_f32 v[28:29], v[68:69], v[152:153] op_sel_hi:[0,1]
	v_pk_mul_f32 v[24:25], v[24:25], v[28:29]
	global_load_dwordx4 v[28:31], v76, s[30:31] offset:16
	global_load_dwordx4 v[32:35], v76, s[30:31]
	global_load_dwordx4 v[36:39], v76, s[30:31] offset:144
	global_load_dwordx4 v[40:43], v76, s[30:31] offset:128
	v_cvt_pk_bf16_f32 v126, v24, v25
	v_pk_mul_f32 v[24:25], v[68:69], v[150:151] op_sel_hi:[0,1]
	v_pk_mul_f32 v[24:25], v[26:27], v[24:25]
	v_pk_mul_f32 v[166:167], v[164:165], v[164:165]
	v_cvt_pk_bf16_f32 v127, v24, v25
	v_pk_mul_f32 v[24:25], v[68:69], v[104:105] op_sel_hi:[0,1]
	v_pk_mul_f32 v[20:21], v[20:21], v[24:25]
	v_and_b32_e32 v151, 0xffff0000, v3
	v_cvt_pk_bf16_f32 v128, v20, v21
	v_pk_mul_f32 v[20:21], v[68:69], v[102:103] op_sel_hi:[0,1]
	v_pk_mul_f32 v[20:21], v[22:23], v[20:21]
	v_lshlrev_b32_e32 v150, 16, v3
	v_cvt_pk_bf16_f32 v129, v20, v21
	v_pk_mul_f32 v[20:21], v[68:69], v[70:71] op_sel_hi:[0,1]
	v_pk_mul_f32 v[16:17], v[16:17], v[20:21]
	v_and_b32_e32 v3, 0xffff0000, v2
	v_cvt_pk_bf16_f32 v130, v16, v17
	v_pk_mul_f32 v[16:17], v[68:69], v[100:101] op_sel_hi:[0,1]
	v_pk_mul_f32 v[16:17], v[18:19], v[16:17]
	v_lshlrev_b32_e32 v2, 16, v2
	v_cvt_pk_bf16_f32 v131, v16, v17
	v_pk_mul_f32 v[16:17], v[68:69], v[98:99] op_sel_hi:[0,1]
	v_pk_mul_f32 v[12:13], v[12:13], v[16:17]
	v_pk_mul_f32 v[160:161], v[2:3], v[2:3]
	v_cvt_pk_bf16_f32 v132, v12, v13
	v_pk_mul_f32 v[12:13], v[68:69], v[96:97] op_sel_hi:[0,1]
	v_pk_mul_f32 v[12:13], v[14:15], v[12:13]
	v_pk_mul_f32 v[154:155], v[150:151], v[150:151]
	v_cvt_pk_bf16_f32 v133, v12, v13
	v_pk_mul_f32 v[12:13], v[68:69], v[94:95] op_sel_hi:[0,1]
	v_pk_mul_f32 v[8:9], v[8:9], v[12:13]
	v_and_b32_e32 v105, 0xffff0000, v5
	v_cvt_pk_bf16_f32 v134, v8, v9
	v_pk_mul_f32 v[8:9], v[68:69], v[92:93] op_sel_hi:[0,1]
	v_pk_mul_f32 v[8:9], v[10:11], v[8:9]
	v_lshlrev_b32_e32 v104, 16, v5
	v_cvt_pk_bf16_f32 v135, v8, v9
	v_pk_mul_f32 v[8:9], v[68:69], v[90:91] op_sel_hi:[0,1]
	s_waitcnt vmcnt(6)
	v_pk_mul_f32 v[8:9], v[142:143], v[8:9]
	v_and_b32_e32 v5, 0xffff0000, v4
	v_cvt_pk_bf16_f32 v136, v8, v9
	v_pk_mul_f32 v[8:9], v[68:69], v[88:89] op_sel_hi:[0,1]
	v_pk_mul_f32 v[8:9], v[144:145], v[8:9]
	v_lshlrev_b32_e32 v4, 16, v4
	v_cvt_pk_bf16_f32 v137, v8, v9
	v_pk_mul_f32 v[8:9], v[68:69], v[86:87] op_sel_hi:[0,1]
	v_pk_mul_f32 v[8:9], v[138:139], v[8:9]
	v_pk_mul_f32 v[142:143], v[104:105], v[104:105]
	v_cvt_pk_bf16_f32 v138, v8, v9
	v_pk_mul_f32 v[8:9], v[68:69], v[84:85] op_sel_hi:[0,1]
	v_pk_mul_f32 v[8:9], v[140:141], v[8:9]
	v_lshlrev_b32_e32 v168, 16, v61
	v_cvt_pk_bf16_f32 v139, v8, v9
	v_pk_mul_f32 v[8:9], v[68:69], v[80:81] op_sel_hi:[0,1]
	s_waitcnt vmcnt(4)
	v_pk_mul_f32 v[8:9], v[146:147], v[8:9]
	v_pk_mul_f32 v[146:147], v[4:5], v[4:5]
	v_cvt_pk_bf16_f32 v140, v8, v9
	v_pk_mul_f32 v[8:9], v[68:69], v[78:79] op_sel_hi:[0,1]
	v_pk_mul_f32 v[70:71], v[148:149], v[8:9]
	v_lshlrev_b64 v[8:9], 7, v[184:185]
	v_lshl_add_u64 v[10:11], s[76:77], 0, v[8:9]
	v_lshl_add_u64 v[12:13], v[10:11], 0, v[76:77]
	global_load_dwordx4 v[44:47], v[12:13], off offset:16
	global_load_dwordx4 v[48:51], v[12:13], off
	v_lshl_add_u64 v[8:9], s[78:79], 0, v[8:9]
	v_lshl_add_u64 v[24:25], v[8:9], 0, v[76:77]
	global_load_dwordx4 v[52:55], v[24:25], off offset:16
	global_load_dwordx4 v[78:81], v[24:25], off
	global_load_dwordx4 v[20:23], v76, s[30:31] offset:80
	global_load_dwordx4 v[82:85], v76, s[30:31] offset:64
	global_load_dwordx4 v[16:19], v76, s[30:31] offset:208
	global_load_dwordx4 v[86:89], v76, s[30:31] offset:192
	global_load_dwordx4 v[8:11], v[12:13], off offset:80
	global_load_dwordx4 v[90:93], v[12:13], off offset:64
	s_nop 0
	global_load_dwordx4 v[12:15], v[24:25], off offset:80
	global_load_dwordx4 v[94:97], v[24:25], off offset:64
	v_add_f32_e32 v69, v172, v173
	v_add_f32_e32 v69, v166, v69
	v_add_f32_e32 v69, v167, v69
	v_add_f32_e32 v69, v160, v69
	v_add_f32_e32 v69, v161, v69
	v_add_f32_e32 v69, v154, v69
	v_add_f32_e32 v69, v155, v69
	v_add_f32_e32 v69, v146, v69
	v_add_f32_e32 v69, v147, v69
	v_and_b32_e32 v25, 0xffff0000, v7
	v_lshlrev_b32_e32 v24, 16, v7
	v_and_b32_e32 v7, 0xffff0000, v6
	v_lshlrev_b32_e32 v6, 16, v6
	v_add_f32_e32 v69, v142, v69
	v_pk_mul_f32 v[100:101], v[6:7], v[6:7]
	v_add_f32_e32 v69, v143, v69
	v_add_f32_e32 v69, v100, v69
	v_pk_mul_f32 v[76:77], v[24:25], v[24:25]
	v_add_f32_e32 v69, v101, v69
	v_and_b32_e32 v61, 0xffff0000, v60
	v_lshlrev_b32_e32 v60, 16, v60
	v_add_f32_e32 v69, v76, v69
	v_pk_mul_f32 v[174:175], v[60:61], v[60:61]
	v_add_f32_e32 v69, v77, v69
	v_add_f32_e32 v69, v174, v69
	v_pk_mul_f32 v[170:171], v[168:169], v[168:169]
	v_add_f32_e32 v69, v175, v69
	v_and_b32_e32 v157, 0xffff0000, v63
	v_lshlrev_b32_e32 v156, 16, v63
	v_and_b32_e32 v63, 0xffff0000, v62
	v_lshlrev_b32_e32 v62, 16, v62
	v_add_f32_e32 v69, v170, v69
	v_pk_mul_f32 v[162:163], v[62:63], v[62:63]
	v_add_f32_e32 v69, v171, v69
	v_add_f32_e32 v69, v162, v69
	v_pk_mul_f32 v[158:159], v[156:157], v[156:157]
	v_add_f32_e32 v69, v163, v69
	v_and_b32_e32 v153, 0xffff0000, v65
	v_lshlrev_b32_e32 v152, 16, v65
	v_and_b32_e32 v65, 0xffff0000, v64
	v_lshlrev_b32_e32 v64, 16, v64
	v_add_f32_e32 v69, v158, v69
	v_pk_mul_f32 v[148:149], v[64:65], v[64:65]
	v_add_f32_e32 v69, v159, v69
	v_add_f32_e32 v69, v148, v69
	v_pk_mul_f32 v[144:145], v[152:153], v[152:153]
	v_add_f32_e32 v69, v149, v69
	v_and_b32_e32 v27, 0xffff0000, v67
	v_lshlrev_b32_e32 v26, 16, v67
	v_and_b32_e32 v67, 0xffff0000, v66
	v_lshlrev_b32_e32 v66, 16, v66
	v_add_f32_e32 v69, v144, v69
	v_pk_mul_f32 v[102:103], v[66:67], v[66:67]
	v_add_f32_e32 v69, v145, v69
	v_add_f32_e32 v69, v102, v69
	v_pk_mul_f32 v[98:99], v[26:27], v[26:27]
	v_add_f32_e32 v69, v103, v69
	v_add_f32_e32 v69, v98, v69
	v_add_f32_e32 v69, v99, v69
	ds_bpermute_b32 v76, v196, v69
	v_cvt_pk_bf16_f32 v141, v70, v71
	v_pk_mul_f32 v[70:71], v[68:69], v[74:75] op_sel_hi:[0,1]
	v_pk_mul_f32 v[56:57], v[56:57], v[70:71]
	s_nop 0
	v_cvt_pk_bf16_f32 v142, v56, v57
	s_waitcnt lgkmcnt(0)
; __device__ __forceinline__ unsigned cvt_pk_bf16(float lo, float hi) { f32x2 v = {lo, hi}; bf16x2_t b = __builtin_convertvector(v, bf16x2_t); return __builtin_bit_cast(unsigned, b); }
; __device__ __forceinline__ float bf2f(unsigned short v) { return __uint_as_float(((unsigned)v) << 16); }
; template <int DQK, bool MOBA>
; __device__ __forceinline__ void attn_unit(const Args& A, int b, int h, int qb, lptr lds) {
;     ...
;             const float scr = __builtin_amdgcn_rsqf(ssr * (1.0f / 64.0f) + 1e-6f);
; #pragma unroll
;             for (int sp = 0; sp < 2; ++sp) {
;                 const int i0 = 16 * sp + 8 * hi;
;                 float o1[8], o2[8];
;                 const f32x4 ga0 = *(const f32x4*)(A.gq_r + i0), ga1 = *(const f32x4*)(A.gq_r + i0 + 4), gb0 = *(const f32x4*)(A.gq_r + 32 + i0), gb1 = *(const f32x4*)(A.gq_r + 32 + i0 + 4);
;                 const f32x4 cc0 = *(const f32x4*)(A.cosT + (size_t)qrow * 32 + i0), cc1 = *(const f32x4*)(A.cosT + (size_t)qrow * 32 + i0 + 4);
;                 const f32x4 ss0 = *(const f32x4*)(A.sinT + (size_t)qrow * 32 + i0), ss1 = *(const f32x4*)(A.sinT + (size_t)qrow * 32 + i0 + 4);
; #pragma unroll
;                 for (int e = 0; e < 8; ++e) {
;                     const float x1 = bf2f((unsigned short)qf[(NS == 12 ? 8 : 0) + sp][e]) * scr * (e < 4 ? ga0[e & 3] : ga1[e & 3]);
;                     const float x2 = bf2f((unsigned short)qf[(NS == 12 ? 10 : 0) + sp][e]) * scr * (e < 4 ? gb0[e & 3] : gb1[e & 3]);
;                     const float c = e < 4 ? cc0[e & 3] : cc1[e & 3], sn = e < 4 ? ss0[e & 3] : ss1[e & 3];
;                     o1[e] = (x1 * c - x2 * sn) * A.qscale; o2[e] = (x2 * c + x1 * sn) * A.qscale;
;                 }
;                 u32x4 w1, w2;
;                 w1.x = cvt_pk_bf16(o1[0], o1[1]); w1.y = cvt_pk_bf16(o1[2], o1[3]); w1.z = cvt_pk_bf16(o1[4], o1[5]); w1.w = cvt_pk_bf16(o1[6], o1[7]);
;                 w2.x = cvt_pk_bf16(o2[0], o2[1]); w2.y = cvt_pk_bf16(o2[2], o2[3]); w2.z = cvt_pk_bf16(o2[4], o2[5]); w2.w = cvt_pk_bf16(o2[6], o2[7]);
;                 qf[(NS == 12 ? 8 : 0) + sp] = __builtin_bit_cast(bf16x8, w1); qf[(NS == 12 ? 10 : 0) + sp] = __builtin_bit_cast(bf16x8, w2);
;     ...
;         float qss = 0.f;
; #pragma unroll
;         for (int s = 0; s < NS; ++s)
; #pragma unroll
;             for (int e = 0; e < 8; ++e) { const float f = bf2f((unsigned short)qf[s][e]); qss += f * f; }
	v_add_f32_e32 v56, v69, v76
	v_fmamk_f32 v56, v56, 0x3c800000, v204
	v_rsq_f32_e32 v56, v56
	v_pk_mul_f32 v[68:69], v[68:69], v[72:73] op_sel_hi:[0,1]
	v_pk_mul_f32 v[58:59], v[58:59], v[68:69]
	v_pk_mul_f32 v[0:1], v[56:57], v[0:1] op_sel_hi:[0,1]
	s_waitcnt vmcnt(14)
	v_pk_mul_f32 v[0:1], v[32:33], v[0:1]
	v_pk_mul_f32 v[32:33], v[56:57], v[60:61] op_sel_hi:[0,1]
	s_waitcnt vmcnt(12)
	v_pk_mul_f32 v[32:33], v[40:41], v[32:33]
	v_pk_mul_f32 v[2:3], v[56:57], v[2:3] op_sel_hi:[0,1]
	s_waitcnt vmcnt(8)
	v_pk_mul_f32 v[40:41], v[78:79], v[32:33]
	v_pk_mul_f32 v[2:3], v[28:29], v[2:3]
	v_pk_fma_f32 v[40:41], v[48:49], v[0:1], v[40:41] neg_lo:[0,0,1] neg_hi:[0,0,1]
	v_pk_mul_f32 v[0:1], v[78:79], v[0:1]
	v_pk_mul_f32 v[28:29], v[56:57], v[62:63] op_sel_hi:[0,1]
	v_pk_fma_f32 v[0:1], v[48:49], v[32:33], v[0:1]
	v_pk_mul_f32 v[32:33], v[56:57], v[164:165] op_sel_hi:[0,1]
	v_pk_mul_f32 v[32:33], v[34:35], v[32:33]
	v_pk_mul_f32 v[34:35], v[56:57], v[168:169] op_sel_hi:[0,1]
	v_pk_mul_f32 v[34:35], v[42:43], v[34:35]
	v_pk_mul_f32 v[28:29], v[36:37], v[28:29]
	v_pk_mul_f32 v[42:43], v[80:81], v[34:35]
	v_pk_mul_f32 v[0:1], v[0:1], s[94:95] op_sel_hi:[1,0]
	v_pk_fma_f32 v[42:43], v[50:51], v[32:33], v[42:43] neg_lo:[0,0,1] neg_hi:[0,0,1]
	v_pk_mul_f32 v[32:33], v[80:81], v[32:33]
	v_cvt_pk_bf16_f32 v144, v0, v1
	v_pk_fma_f32 v[32:33], v[50:51], v[34:35], v[32:33]
	v_pk_mul_f32 v[34:35], v[52:53], v[28:29]
	v_pk_mul_f32 v[0:1], v[56:57], v[4:5] op_sel_hi:[0,1]
	v_pk_fma_f32 v[34:35], v[44:45], v[2:3], v[34:35] neg_lo:[0,0,1] neg_hi:[0,0,1]
	v_pk_mul_f32 v[2:3], v[52:53], v[2:3]
	s_waitcnt vmcnt(6)
	v_pk_mul_f32 v[0:1], v[82:83], v[0:1]
	v_pk_fma_f32 v[2:3], v[44:45], v[28:29], v[2:3]
	v_pk_mul_f32 v[28:29], v[56:57], v[150:151] op_sel_hi:[0,1]
	v_pk_mul_f32 v[2:3], v[2:3], s[94:95] op_sel_hi:[1,0]
	v_pk_mul_f32 v[28:29], v[30:31], v[28:29]
	v_pk_mul_f32 v[30:31], v[56:57], v[156:157] op_sel_hi:[0,1]
	v_cvt_pk_bf16_f32 v146, v2, v3
	v_pk_mul_f32 v[2:3], v[56:57], v[64:65] op_sel_hi:[0,1]
	v_pk_mul_f32 v[30:31], v[38:39], v[30:31]
	s_waitcnt vmcnt(4)
	v_pk_mul_f32 v[2:3], v[86:87], v[2:3]
	v_pk_mul_f32 v[36:37], v[54:55], v[30:31]
	s_waitcnt vmcnt(0)
	v_pk_mul_f32 v[4:5], v[94:95], v[2:3]
	v_pk_fma_f32 v[36:37], v[46:47], v[28:29], v[36:37] neg_lo:[0,0,1] neg_hi:[0,0,1]
	v_pk_mul_f32 v[28:29], v[54:55], v[28:29]
	v_pk_fma_f32 v[4:5], v[90:91], v[0:1], v[4:5] neg_lo:[0,0,1] neg_hi:[0,0,1]
	v_pk_mul_f32 v[0:1], v[94:95], v[0:1]
	v_pk_fma_f32 v[28:29], v[46:47], v[30:31], v[28:29]
	v_pk_fma_f32 v[0:1], v[90:91], v[2:3], v[0:1]
	v_pk_mul_f32 v[28:29], v[28:29], s[94:95] op_sel_hi:[1,0]
	v_pk_mul_f32 v[0:1], v[0:1], s[94:95] op_sel_hi:[1,0]
	v_cvt_pk_bf16_f32 v147, v28, v29
	v_pk_mul_f32 v[28:29], v[56:57], v[152:153] op_sel_hi:[0,1]
	v_cvt_pk_bf16_f32 v152, v0, v1
	v_and_b32_e32 v0, 0xffff0000, v112
	v_lshlrev_b32_e32 v1, 16, v112
	v_mul_f32_e32 v0, v0, v0
	v_fmac_f32_e32 v0, v1, v1
	v_lshlrev_b32_e32 v1, 16, v113
	v_fmac_f32_e32 v0, v1, v1
	v_and_b32_e32 v1, 0xffff0000, v113
	v_fmac_f32_e32 v0, v1, v1
	v_lshlrev_b32_e32 v1, 16, v114
	v_fmac_f32_e32 v0, v1, v1
	v_and_b32_e32 v1, 0xffff0000, v114
	v_fmac_f32_e32 v0, v1, v1
	v_lshlrev_b32_e32 v1, 16, v115
	v_fmac_f32_e32 v0, v1, v1
	v_and_b32_e32 v1, 0xffff0000, v115
	v_fmac_f32_e32 v0, v1, v1
	v_lshlrev_b32_e32 v1, 16, v116
	v_fmac_f32_e32 v0, v1, v1
	v_and_b32_e32 v1, 0xffff0000, v116
	v_fmac_f32_e32 v0, v1, v1
	v_lshlrev_b32_e32 v1, 16, v117
	v_fmac_f32_e32 v0, v1, v1
	v_and_b32_e32 v1, 0xffff0000, v117
	v_fmac_f32_e32 v0, v1, v1
	v_lshlrev_b32_e32 v1, 16, v118
	v_fmac_f32_e32 v0, v1, v1
	v_and_b32_e32 v1, 0xffff0000, v118
	v_fmac_f32_e32 v0, v1, v1
	v_lshlrev_b32_e32 v1, 16, v119
	v_fmac_f32_e32 v0, v1, v1
	v_and_b32_e32 v1, 0xffff0000, v119
	v_fmac_f32_e32 v0, v1, v1
	v_lshlrev_b32_e32 v1, 16, v120
	v_fmac_f32_e32 v0, v1, v1
	v_and_b32_e32 v1, 0xffff0000, v120
	v_fmac_f32_e32 v0, v1, v1
	v_lshlrev_b32_e32 v1, 16, v121
	v_fmac_f32_e32 v0, v1, v1
	v_and_b32_e32 v1, 0xffff0000, v121
	v_fmac_f32_e32 v0, v1, v1
	v_lshlrev_b32_e32 v1, 16, v122
	v_fmac_f32_e32 v0, v1, v1
	v_and_b32_e32 v1, 0xffff0000, v122
	v_fmac_f32_e32 v0, v1, v1
	v_lshlrev_b32_e32 v1, 16, v123
	v_fmac_f32_e32 v0, v1, v1
	v_and_b32_e32 v1, 0xffff0000, v123
	v_fmac_f32_e32 v0, v1, v1
	v_lshlrev_b32_e32 v1, 16, v124
	v_fmac_f32_e32 v0, v1, v1
	v_and_b32_e32 v1, 0xffff0000, v124
	v_fmac_f32_e32 v0, v1, v1
	v_lshlrev_b32_e32 v1, 16, v125
	v_fmac_f32_e32 v0, v1, v1
	v_and_b32_e32 v1, 0xffff0000, v125
	v_fmac_f32_e32 v0, v1, v1
	v_lshlrev_b32_e32 v1, 16, v126
	v_fmac_f32_e32 v0, v1, v1
	v_and_b32_e32 v1, 0xffff0000, v126
	v_fmac_f32_e32 v0, v1, v1
	v_lshlrev_b32_e32 v1, 16, v127
	v_fmac_f32_e32 v0, v1, v1
	v_and_b32_e32 v1, 0xffff0000, v127
	v_fmac_f32_e32 v0, v1, v1
	v_lshlrev_b32_e32 v1, 16, v128
	v_fmac_f32_e32 v0, v1, v1
	v_and_b32_e32 v1, 0xffff0000, v128
	v_fmac_f32_e32 v0, v1, v1
	v_lshlrev_b32_e32 v1, 16, v129
	v_fmac_f32_e32 v0, v1, v1
	v_and_b32_e32 v1, 0xffff0000, v129
	v_fmac_f32_e32 v0, v1, v1
	v_lshlrev_b32_e32 v1, 16, v130
	v_fmac_f32_e32 v0, v1, v1
	v_and_b32_e32 v1, 0xffff0000, v130
	v_fmac_f32_e32 v0, v1, v1
	v_lshlrev_b32_e32 v1, 16, v131
	v_fmac_f32_e32 v0, v1, v1
	v_and_b32_e32 v1, 0xffff0000, v131
	v_fmac_f32_e32 v0, v1, v1
	v_lshlrev_b32_e32 v1, 16, v132
	v_fmac_f32_e32 v0, v1, v1
	v_and_b32_e32 v1, 0xffff0000, v132
	v_fmac_f32_e32 v0, v1, v1
	v_lshlrev_b32_e32 v1, 16, v133
	v_fmac_f32_e32 v0, v1, v1
	v_and_b32_e32 v1, 0xffff0000, v133
	v_fmac_f32_e32 v0, v1, v1
	v_lshlrev_b32_e32 v1, 16, v134
	v_fmac_f32_e32 v0, v1, v1
	v_and_b32_e32 v1, 0xffff0000, v134
	v_fmac_f32_e32 v0, v1, v1
	v_lshlrev_b32_e32 v1, 16, v135
; __device__ __forceinline__ float bf2f(unsigned short v) { return __uint_as_float(((unsigned)v) << 16); }
; template <int DQK, bool MOBA>
; __device__ __forceinline__ void attn_unit(const Args& A, int b, int h, int qb, lptr lds) {
;     ...
;         float qss = 0.f;
; #pragma unroll
;         for (int s = 0; s < NS; ++s)
; #pragma unroll
;             for (int e = 0; e < 8; ++e) { const float f = bf2f((unsigned short)qf[s][e]); qss += f * f; }
;         qss += __shfl_xor(qss, 32);
;         float gmx = fmaxf(fabsf(A.gk_n[lane]), fabsf(A.gk_n[lane + 64]));
;         float grx = (DQK == 192) ? fabsf(A.gk_r[lane]) : 0.f;
;         float bmx = (MOBA && lane < 32) ? fabsf(A.relb[lane * 8 + h]) * 1.4426950408889634f : 0.f;
; #pragma unroll
;         for (int o_ = 1; o_ < 64; o_ <<= 1) { gmx = fmaxf(gmx, __shfl_xor(gmx, o_)); grx = fmaxf(grx, __shfl_xor(grx, o_)); bmx = fmaxf(bmx, __shfl_xor(bmx, o_)); }
	v_fmac_f32_e32 v0, v1, v1
	v_and_b32_e32 v1, 0xffff0000, v135
	v_fmac_f32_e32 v0, v1, v1
	v_lshlrev_b32_e32 v1, 16, v136
	v_fmac_f32_e32 v0, v1, v1
	v_and_b32_e32 v1, 0xffff0000, v136
	v_fmac_f32_e32 v0, v1, v1
	v_lshlrev_b32_e32 v1, 16, v137
	v_fmac_f32_e32 v0, v1, v1
	v_and_b32_e32 v1, 0xffff0000, v137
	v_pk_mul_f32 v[6:7], v[56:57], v[6:7] op_sel_hi:[0,1]
	v_fmac_f32_e32 v0, v1, v1
	v_lshlrev_b32_e32 v1, 16, v138
	v_pk_mul_f32 v[4:5], v[4:5], s[94:95] op_sel_hi:[1,0]
	v_pk_mul_f32 v[6:7], v[20:21], v[6:7]
	v_pk_mul_f32 v[20:21], v[56:57], v[66:67] op_sel_hi:[0,1]
	v_fmac_f32_e32 v0, v1, v1
	v_lshlrev_b32_e32 v1, 2, v110
	v_pk_mul_f32 v[16:17], v[16:17], v[20:21]
	v_cvt_pk_bf16_f32 v156, v4, v5
	global_load_dword v4, v1, s[38:39]
	global_load_dword v5, v1, s[38:39] offset:256
	v_pk_mul_f32 v[20:21], v[12:13], v[16:17]
	v_pk_mul_f32 v[2:3], v[56:57], v[104:105] op_sel_hi:[0,1]
	v_pk_fma_f32 v[20:21], v[8:9], v[6:7], v[20:21] neg_lo:[0,0,1] neg_hi:[0,0,1]
	v_pk_mul_f32 v[6:7], v[12:13], v[6:7]
	v_pk_mul_f32 v[28:29], v[88:89], v[28:29]
	v_pk_fma_f32 v[6:7], v[8:9], v[16:17], v[6:7]
	v_pk_mul_f32 v[2:3], v[84:85], v[2:3]
	v_pk_mul_f32 v[6:7], v[6:7], s[94:95] op_sel_hi:[1,0]
	v_pk_mul_f32 v[30:31], v[96:97], v[28:29]
	v_cvt_pk_bf16_f32 v154, v6, v7
	global_load_dword v6, v1, s[40:41]
	v_pk_fma_f32 v[30:31], v[92:93], v[2:3], v[30:31] neg_lo:[0,0,1] neg_hi:[0,0,1]
	v_pk_mul_f32 v[2:3], v[96:97], v[2:3]
	v_and_b32_e32 v1, 0xffff0000, v140
	v_pk_fma_f32 v[2:3], v[92:93], v[28:29], v[2:3]
	v_cvt_pk_bf16_f32 v143, v58, v59
	v_pk_mul_f32 v[2:3], v[2:3], s[94:95] op_sel_hi:[1,0]
	v_pk_mul_f32 v[40:41], v[40:41], s[94:95] op_sel_hi:[1,0]
	v_cvt_pk_bf16_f32 v153, v2, v3
	v_and_b32_e32 v2, 0xffff0000, v138
	v_fmac_f32_e32 v0, v2, v2
	v_lshlrev_b32_e32 v2, 16, v139
	v_fmac_f32_e32 v0, v2, v2
	v_and_b32_e32 v2, 0xffff0000, v139
	v_fmac_f32_e32 v0, v2, v2
	v_lshlrev_b32_e32 v2, 16, v140
	v_fmac_f32_e32 v0, v2, v2
	v_fmac_f32_e32 v0, v1, v1
	v_lshlrev_b32_e32 v1, 16, v141
	v_fmac_f32_e32 v0, v1, v1
	v_and_b32_e32 v1, 0xffff0000, v141
	v_fmac_f32_e32 v0, v1, v1
	v_lshlrev_b32_e32 v1, 16, v142
	v_fmac_f32_e32 v0, v1, v1
	v_and_b32_e32 v1, 0xffff0000, v142
	v_fmac_f32_e32 v0, v1, v1
	v_lshlrev_b32_e32 v1, 16, v143
	v_cvt_pk_bf16_f32 v148, v40, v41
	v_fmac_f32_e32 v0, v1, v1
	v_and_b32_e32 v1, 0xffff0000, v143
	v_pk_mul_f32 v[42:43], v[42:43], s[94:95] op_sel_hi:[1,0]
	v_fmac_f32_e32 v0, v1, v1
	v_lshlrev_b32_e32 v1, 16, v148
	v_cvt_pk_bf16_f32 v149, v42, v43
	v_fmac_f32_e32 v0, v1, v1
	v_and_b32_e32 v1, 0xffff0000, v148
	v_pk_mul_f32 v[34:35], v[34:35], s[94:95] op_sel_hi:[1,0]
	v_fmac_f32_e32 v0, v1, v1
	v_lshlrev_b32_e32 v1, 16, v149
	v_cvt_pk_bf16_f32 v150, v34, v35
	v_fmac_f32_e32 v0, v1, v1
	v_and_b32_e32 v1, 0xffff0000, v149
	v_pk_mul_f32 v[36:37], v[36:37], s[94:95] op_sel_hi:[1,0]
	v_fmac_f32_e32 v0, v1, v1
	v_lshlrev_b32_e32 v1, 16, v150
	v_cvt_pk_bf16_f32 v151, v36, v37
	v_fmac_f32_e32 v0, v1, v1
	v_and_b32_e32 v1, 0xffff0000, v150
	v_fmac_f32_e32 v0, v1, v1
	v_lshlrev_b32_e32 v1, 16, v151
	v_fmac_f32_e32 v0, v1, v1
	v_and_b32_e32 v1, 0xffff0000, v151
	v_pk_mul_f32 v[30:31], v[30:31], s[94:95] op_sel_hi:[1,0]
	v_pk_mul_f32 v[12:13], v[56:57], v[26:27] op_sel_hi:[0,1]
	v_fmac_f32_e32 v0, v1, v1
	v_lshlrev_b32_e32 v1, 16, v156
	v_pk_mul_f32 v[8:9], v[56:57], v[24:25] op_sel_hi:[0,1]
	v_pk_mul_f32 v[12:13], v[18:19], v[12:13]
	v_cvt_pk_bf16_f32 v157, v30, v31
	v_fmac_f32_e32 v0, v1, v1
	v_and_b32_e32 v1, 0xffff0000, v156
	v_pk_mul_f32 v[20:21], v[20:21], s[94:95] op_sel_hi:[1,0]
	v_pk_mul_f32 v[8:9], v[22:23], v[8:9]
	v_pk_mul_f32 v[16:17], v[14:15], v[12:13]
	v_fmac_f32_e32 v0, v1, v1
	v_lshlrev_b32_e32 v1, 16, v157
	v_pk_fma_f32 v[16:17], v[10:11], v[8:9], v[16:17] neg_lo:[0,0,1] neg_hi:[0,0,1]
	v_cvt_pk_bf16_f32 v158, v20, v21
	v_fmac_f32_e32 v0, v1, v1
	v_and_b32_e32 v1, 0xffff0000, v157
	v_pk_mul_f32 v[16:17], v[16:17], s[94:95] op_sel_hi:[1,0]
	v_fmac_f32_e32 v0, v1, v1
	v_lshlrev_b32_e32 v1, 16, v158
	v_cvt_pk_bf16_f32 v159, v16, v17
	v_fmac_f32_e32 v0, v1, v1
	v_and_b32_e32 v1, 0xffff0000, v158
	v_fmac_f32_e32 v0, v1, v1
	v_lshlrev_b32_e32 v1, 16, v159
	v_pk_mul_f32 v[32:33], v[32:33], s[94:95] op_sel_hi:[1,0]
	v_fmac_f32_e32 v0, v1, v1
	v_and_b32_e32 v1, 0xffff0000, v159
	v_cvt_pk_bf16_f32 v145, v32, v33
	v_fmac_f32_e32 v0, v1, v1
	v_lshlrev_b32_e32 v1, 16, v144
	v_fmac_f32_e32 v0, v1, v1
	v_and_b32_e32 v1, 0xffff0000, v144
	v_and_b32_e32 v3, 0xffff0000, v145
	v_lshlrev_b32_e32 v2, 16, v145
	v_fmac_f32_e32 v0, v1, v1
	v_pk_mul_f32 v[2:3], v[2:3], v[2:3]
	v_and_b32_e32 v1, 0xffff0000, v146
	v_add_f32_e32 v0, v2, v0
	v_add_f32_e32 v2, v3, v0
	v_lshlrev_b32_e32 v0, 16, v146
	v_pk_mul_f32 v[0:1], v[0:1], v[0:1]
	v_pk_mul_f32 v[8:9], v[14:15], v[8:9]
	v_add_f32_e32 v0, v0, v2
	v_add_f32_e32 v2, v1, v0
	v_lshlrev_b32_e32 v1, 16, v147
	v_and_b32_e32 v0, 0xffff0000, v147
	v_pk_mul_f32 v[0:1], v[0:1], v[0:1]
	v_pk_fma_f32 v[8:9], v[10:11], v[12:13], v[8:9]
	v_add_f32_e32 v1, v1, v2
	v_add_f32_e32 v2, v0, v1
	v_and_b32_e32 v1, 0xffff0000, v152
	v_lshlrev_b32_e32 v0, 16, v152
	v_pk_mul_f32 v[0:1], v[0:1], v[0:1]
	v_pk_mul_f32 v[8:9], v[8:9], s[94:95] op_sel_hi:[1,0]
	v_add_f32_e32 v0, v0, v2
	v_add_f32_e32 v2, v1, v0
	s_waitcnt vmcnt(1)
	v_max_f32_e64 v0, |v5|, |v5|
	v_max_f32_e64 v1, |v4|, |v4|
	v_max_f32_e32 v3, v1, v0
	v_xor_b32_e32 v0, 1, v206
	v_cmp_lt_i32_e32 vcc, v0, v109
	s_waitcnt vmcnt(0)
	v_and_b32_e32 v1, 0x7fffffff, v6
	v_cvt_pk_bf16_f32 v155, v8, v9
	v_cndmask_b32_e32 v0, v206, v0, vcc
	v_lshlrev_b32_e32 v0, 2, v0
	ds_bpermute_b32 v4, v0, v3
	ds_bpermute_b32 v5, v0, v1
	v_and_b32_e32 v1, 0xffff0000, v153
	v_lshlrev_b32_e32 v0, 16, v153
	v_pk_mul_f32 v[0:1], v[0:1], v[0:1]
	s_waitcnt lgkmcnt(1)
; template <int DQK, bool MOBA>
; __device__ __forceinline__ void attn_unit(const Args& A, int b, int h, int qb, lptr lds) {
;     ...
;         qss += __shfl_xor(qss, 32);
;         float gmx = fmaxf(fabsf(A.gk_n[lane]), fabsf(A.gk_n[lane + 64]));
;         float grx = (DQK == 192) ? fabsf(A.gk_r[lane]) : 0.f;
;         float bmx = (MOBA && lane < 32) ? fabsf(A.relb[lane * 8 + h]) * 1.4426950408889634f : 0.f;
; #pragma unroll
;         for (int o_ = 1; o_ < 64; o_ <<= 1) { gmx = fmaxf(gmx, __shfl_xor(gmx, o_)); grx = fmaxf(grx, __shfl_xor(grx, o_)); bmx = fmaxf(bmx, __shfl_xor(bmx, o_)); }
;         negm = -(sqrtf(qss * (128.0f * gmx * gmx + 64.0f * grx * grx)) * 1.01f + bmx + 0.01f);
	v_max_f32_e32 v4, v4, v4
	v_max_f32_e32 v3, v3, v4
	s_waitcnt lgkmcnt(0)
	v_max_f32_e32 v4, v5, v5
	v_max_f32_e64 v5, |v6|, |v6|
	v_xor_b32_e32 v6, 2, v206
	v_cmp_lt_i32_e32 vcc, v6, v109
	v_max_f32_e32 v4, v5, v4
	v_add_f32_e32 v0, v0, v2
	v_cndmask_b32_e32 v6, v206, v6, vcc
	v_lshlrev_b32_e32 v6, 2, v6
	ds_bpermute_b32 v7, v6, v3
	ds_bpermute_b32 v5, v6, v4
	v_and_b32_e32 v32, 15, v106
	v_lshlrev_b32_e32 v186, 4, v32
	v_add_u32_e32 v14, s4, v199
	s_waitcnt lgkmcnt(1)
	v_max_f32_e32 v2, v7, v7
	v_max_f32_e32 v2, v3, v2
	s_waitcnt lgkmcnt(0)
	v_max_f32_e32 v3, v5, v5
	v_xor_b32_e32 v5, 4, v206
	v_cmp_lt_i32_e32 vcc, v5, v109
	v_max_f32_e32 v3, v4, v3
	v_ashrrev_i32_e32 v15, 31, v14
	v_cndmask_b32_e32 v5, v206, v5, vcc
	v_lshlrev_b32_e32 v5, 2, v5
	ds_bpermute_b32 v6, v5, v2
	ds_bpermute_b32 v4, v5, v3
	v_add_f32_e32 v5, v1, v0
	v_and_b32_e32 v1, 0xffff0000, v154
	v_lshlrev_b64 v[14:15], 7, v[14:15]
	s_waitcnt lgkmcnt(1)
	v_max_f32_e32 v0, v6, v6
	v_max_f32_e32 v2, v2, v0
	s_waitcnt lgkmcnt(0)
	v_max_f32_e32 v0, v4, v4
	v_xor_b32_e32 v4, 8, v206
	v_cmp_lt_i32_e32 vcc, v4, v109
	v_max_f32_e32 v3, v3, v0
	v_lshlrev_b32_e32 v0, 16, v154
	v_cndmask_b32_e32 v4, v206, v4, vcc
	v_lshlrev_b32_e32 v4, 2, v4
	ds_bpermute_b32 v6, v4, v2
	ds_bpermute_b32 v4, v4, v3
	v_pk_mul_f32 v[0:1], v[0:1], v[0:1]
	v_lshlrev_b32_e32 v16, 4, v106
	v_add_f32_e32 v0, v0, v5
	s_waitcnt lgkmcnt(1)
	v_max_f32_e32 v6, v6, v6
	v_max_f32_e32 v2, v2, v6
	v_xor_b32_e32 v6, 16, v206
	v_cmp_lt_i32_e32 vcc, v6, v109
	s_waitcnt lgkmcnt(0)
	v_max_f32_e32 v4, v4, v4
	v_max_f32_e32 v3, v3, v4
	v_cndmask_b32_e32 v6, v206, v6, vcc
	v_lshlrev_b32_e32 v6, 2, v6
	ds_bpermute_b32 v7, v6, v2
	ds_bpermute_b32 v4, v6, v3
	v_add_f32_e32 v1, v1, v0
	v_and_b32_e32 v5, 0xffff0000, v155
	v_lshl_add_u64 v[14:15], s[86:87], 0, v[14:15]
	s_waitcnt lgkmcnt(1)
	v_max_f32_e32 v0, v7, v7
	v_max_f32_e32 v0, v2, v0
	s_waitcnt lgkmcnt(0)
	v_max_f32_e32 v2, v4, v4
	ds_bpermute_b32 v4, v196, v0
	v_max_f32_e32 v6, v3, v2
	ds_bpermute_b32 v7, v196, v6
	v_lshlrev_b32_e32 v3, 16, v155
	v_mov_b32_e32 v183, v3
	s_waitcnt lgkmcnt(1)
	v_max_f32_e32 v2, v4, v4
	v_max_f32_e32 v2, v0, v2
	s_waitcnt lgkmcnt(0)
	v_max_f32_e32 v0, v7, v7
	v_max_f32_e32 v4, v6, v0
	v_pk_mul_f32 v[8:9], v[2:3], v[182:183]
	v_mov_b32_e32 v0, v2
	v_pk_mul_f32 v[8:9], v[2:3], v[8:9]
	v_pk_fma_f32 v[0:1], v[2:3], v[182:183], v[0:1]
	v_mul_f32_e32 v6, 0x42800000, v4
	v_mov_b32_e32 v9, v1
	v_mov_b32_e32 v7, v5
	v_pk_fma_f32 v[26:27], v[4:5], v[6:7], v[8:9]
	ds_bpermute_b32 v30, v196, v27
	v_ashrrev_i32_e32 v0, 4, v106
	v_ashrrev_i32_e32 v1, 31, v0
	v_lshlrev_b64 v[2:3], 11, v[0:1]
	v_lshl_add_u64 v[4:5], s[0:1], 0, v[2:3]
	s_waitcnt lgkmcnt(0)
; template <int DQK, bool MOBA>
; __device__ __forceinline__ void attn_unit(const Args& A, int b, int h, int qb, lptr lds) {
;     ...
;         negm = -(sqrtf(qss * (128.0f * gmx * gmx + 64.0f * grx * grx)) * 1.01f + bmx + 0.01f);
;     }
;     const int NT = 4 * (own + 1);
;     u32x4 kr0, kr1, kr2, vr0, vr1; int pkr = 0;
;     kr2 = (u32x4){0u, 0u, 0u, 0u};
;     ...
;     f32x16 o[4];
; #pragma unroll
;     for (int d = 0; d < 4; ++d)
; #pragma unroll
;         for (int r = 0; r < 16; ++r) o[d][r] = 0.f;
;     float lrow = 0.f;
;     ATT_LOAD(0); ATT_WRITE(0);
;     if (NT > 1) ATT_LOAD(1);
;     __syncthreads();
;     for (int t = 0; t < NT; ++t) {
;         const int buf = t & 1;
;         if (t + 1 < NT) { ATT_WRITE(buf ^ 1); if (t + 2 < NT) ATT_LOAD(t + 2); }
	v_add_f32_e32 v27, v27, v30
	v_mul_f32_e32 v26, v26, v27
	v_mul_f32_e32 v27, 0x4f800000, v26
	v_cmp_gt_f32_e32 vcc, s35, v26
	v_lshl_add_u64 v[6:7], v[4:5], 0, v[186:187]
	v_add_u32_e32 v4, 32, v0
	v_cndmask_b32_e32 v26, v26, v27, vcc
	v_ashrrev_i32_e32 v5, 31, v4
	v_sqrt_f32_e32 v27, v26
	v_lshlrev_b64 v[28:29], 11, v[4:5]
	v_lshl_add_u64 v[8:9], s[0:1], 0, v[28:29]
	s_add_u32 s0, s92, s44
	s_addc_u32 s1, s93, s45
	s_add_u32 s0, s0, s6
	v_add_u32_e32 v30, -1, v27
	s_addc_u32 s1, s1, s7
	v_fma_f32 v31, -v30, v27, v26
	v_lshl_add_u64 v[18:19], s[0:1], 0, v[2:3]
	v_lshl_add_u64 v[22:23], s[0:1], 0, v[28:29]
	v_cmp_ge_f32_e64 s[0:1], 0, v31
	v_add_u32_e32 v31, 1, v27
	v_and_b32_e32 v188, 0x70, v16
	v_cndmask_b32_e64 v30, v27, v30, s[0:1]
	v_fma_f32 v27, -v31, v27, v26
	v_cmp_lt_f32_e64 s[0:1], 0, v27
	v_lshl_add_u64 v[10:11], v[8:9], 0, v[186:187]
	v_lshl_add_u64 v[14:15], v[14:15], 0, v[188:189]
	v_cndmask_b32_e64 v27, v30, v31, s[0:1]
	v_mul_f32_e32 v30, 0x37800000, v27
	v_cndmask_b32_e32 v27, v27, v30, vcc
	v_cmp_class_f32_e32 vcc, v26, v205
	s_mov_b32 s0, 0x3f8147ae
	global_load_dwordx4 v[6:9], v[6:7], off
	s_nop 0
	global_load_dwordx4 v[10:13], v[10:11], off
	v_cndmask_b32_e32 v26, v27, v26, vcc
	v_fma_f32 v26, v26, s0, 0
	v_add_f32_e32 v33, 0x3c23d70a, v26
	v_mov_b32_e32 v26, s15
	s_movk_i32 s0, 0xffe0
	v_bfi_b32 v197, s0, v26, v106
	s_or_b32 s0, s4, 64
	s_ashr_i32 s1, s0, 31
	s_lshl_b64 s[44:45], s[0:1], 11
	s_add_u32 s1, s92, s44
	s_addc_u32 s4, s93, s45
	s_add_u32 s46, s1, s6
	global_load_dwordx4 v[14:17], v[14:15], off
	v_lshl_add_u64 v[22:23], v[22:23], 0, v[186:187]
	s_addc_u32 s47, s4, s7
	global_load_dwordx4 v[22:25], v[22:23], off
	v_lshl_add_u64 v[26:27], s[46:47], 0, v[28:29]
	v_add_u32_e32 v30, s0, v199
	s_add_u32 s0, s90, s44
	v_lshl_add_u64 v[18:19], v[18:19], 0, v[186:187]
	v_lshl_add_u64 v[26:27], v[26:27], 0, v[186:187]
	v_ashrrev_i32_e32 v31, 31, v30
	s_addc_u32 s1, s91, s45
	global_load_dwordx4 v[18:21], v[18:19], off
	v_lshlrev_b64 v[30:31], 7, v[30:31]
	global_load_dwordx4 v[160:163], v[26:27], off
	v_lshl_add_u64 v[26:27], s[46:47], 0, v[2:3]
	s_add_u32 s0, s0, s6
	v_lshl_add_u64 v[26:27], v[26:27], 0, v[186:187]
	v_lshl_add_u64 v[30:31], s[86:87], 0, v[30:31]
	s_addc_u32 s1, s1, s7
	v_lshl_add_u64 v[30:31], v[30:31], 0, v[188:189]
	global_load_dwordx4 v[164:167], v[26:27], off
	global_load_dwordx4 v[172:175], v[30:31], off
	v_lshl_add_u64 v[26:27], s[0:1], 0, v[28:29]
	v_lshl_add_u64 v[26:27], v[26:27], 0, v[186:187]
	v_lshl_add_u64 v[2:3], s[0:1], 0, v[2:3]
	v_lshl_add_u64 v[2:3], v[2:3], 0, v[186:187]
	global_load_dwordx4 v[168:171], v[26:27], off
	global_load_dwordx4 v[176:179], v[2:3], off
	s_movk_i32 s0, 0x190
	v_mul_lo_u32 v200, v0, s0
	v_mul_lo_u32 v210, v199, s0
	s_movk_i32 s0, 0xffb0
	v_lshlrev_b64 v[26:27], 10, v[0:1]
	v_add3_u32 v1, 0, v200, v186
	v_add3_u32 v2, 0, v210, v188
	v_mul_lo_u32 v211, v0, s12
	v_mul_lo_u32 v0, v0, s0
	s_movk_i32 s0, 0x3200
	v_lshlrev_b32_e32 v183, 2, v107
	s_add_u32 s4, s90, s6
	v_lshlrev_b32_e32 v28, 3, v32
	v_lshlrev_b64 v[30:31], 10, v[4:5]
	s_addc_u32 s15, s91, s7
	v_xor_b32_e32 v64, 0x80000000, v33
	s_add_u32 s6, s92, s6
	v_mov_b32_e32 v3, v181
	v_mov_b32_e32 v4, v181
	v_mov_b32_e32 v5, v181
	v_lshlrev_b64 v[192:193], 1, v[26:27]
	v_lshlrev_b64 v[194:195], 1, v[30:31]
	v_add_u32_e32 v201, 0x3200, v200
	v_add_u32_e32 v212, 0x2800, v211
	v_mov_b32_e32 v65, v64
	v_mov_b32_e32 v66, v64
	v_mov_b32_e32 v67, v64
	v_mov_b32_e32 v68, v64
	v_mov_b32_e32 v69, v64
	v_mov_b32_e32 v70, v64
	v_mov_b32_e32 v71, v64
	v_mov_b32_e32 v72, v64
	v_mov_b32_e32 v73, v64
	v_mov_b32_e32 v74, v64
	v_mov_b32_e32 v75, v64
	v_mov_b32_e32 v76, v64
	v_mov_b32_e32 v77, v64
	v_mov_b32_e32 v78, v64
	v_mov_b32_e32 v79, v64
	v_lshl_add_u64 v[190:191], s[86:87], 0, v[188:189]
	s_waitcnt vmcnt(9)
	ds_write_b128 v1, v[6:9]
	s_waitcnt vmcnt(8)
	ds_write_b128 v1, v[10:13] offset:12800
	v_mov_b32_e32 v6, v181
	v_mov_b32_e32 v7, v181
	v_mov_b32_e32 v8, v181
	v_mov_b32_e32 v9, v181
	v_mov_b32_e32 v10, v181
	v_mov_b32_e32 v11, v181
	v_mov_b32_e32 v12, v181
	v_mov_b32_e32 v13, v181
	s_addc_u32 s7, s93, s7
	s_or_b32 s13, s13, 0xc0
	v_mov_b32_e32 v187, 0
	s_waitcnt vmcnt(7)
	ds_write_b128 v2, v[14:17] offset:256
	v_add_u32_e32 v2, v1, v0
	v_add3_u32 v0, v1, s0, v0
	s_waitcnt vmcnt(6)
	ds_write_b128 v0, v[22:25] offset:48640
	v_mul_u32_u24_e32 v0, 0x190, v108
	v_add3_u32 v213, 0, v0, v180
	v_lshrrev_b32_e32 v0, 2, v106
	v_and_or_b32 v0, v0, 3, v183
	v_lshlrev_b32_e32 v1, 1, v106
	v_mad_u32_u24 v0, v0, s12, 0
	v_and_b32_e32 v1, 32, v1
	s_waitcnt vmcnt(5)
	ds_write_b128 v2, v[18:21] offset:51200
	v_lshlrev_b32_e32 v2, 3, v106
	v_and_b32_e32 v2, 24, v2
	v_mov_b32_e32 v14, v181
	v_mov_b32_e32 v15, v181
	v_add3_u32 v198, v0, v1, v2
	v_mov_b32_e32 v0, v181
	v_mov_b32_e32 v1, v181
	v_mov_b32_e32 v2, v181
	v_lshlrev_b32_e32 v180, 1, v28
	v_mov_b64_e32 v[30:31], v[14:15]
	v_mov_b64_e32 v[46:47], v[14:15]
	v_mov_b64_e32 v[62:63], v[14:15]
	v_mov_b64_e32 v[28:29], v[12:13]
	v_mov_b64_e32 v[26:27], v[10:11]
	v_mov_b64_e32 v[24:25], v[8:9]
	v_mov_b64_e32 v[22:23], v[6:7]
	v_mov_b64_e32 v[20:21], v[4:5]
	v_mov_b64_e32 v[18:19], v[2:3]
	v_mov_b64_e32 v[16:17], v[0:1]
	v_mov_b64_e32 v[44:45], v[12:13]
	v_mov_b64_e32 v[42:43], v[10:11]
	v_mov_b64_e32 v[40:41], v[8:9]
	v_mov_b64_e32 v[38:39], v[6:7]
	v_mov_b64_e32 v[36:37], v[4:5]
	v_mov_b64_e32 v[34:35], v[2:3]
	v_mov_b64_e32 v[32:33], v[0:1]
	v_mov_b64_e32 v[60:61], v[12:13]
	v_mov_b64_e32 v[58:59], v[10:11]
	v_mov_b64_e32 v[56:57], v[8:9]
	v_mov_b64_e32 v[54:55], v[6:7]
	v_mov_b64_e32 v[52:53], v[4:5]
	v_mov_b64_e32 v[50:51], v[2:3]
	v_mov_b64_e32 v[48:49], v[0:1]
	s_waitcnt vmcnt(0) lgkmcnt(0)
	s_barrier
	s_cmp_lt_u32 s23, 0x80
	s_cbranch_scc1 .LBB0_812
	s_barrier
	s_branch .LBB0_812
.LBB0_810:
	s_waitcnt lgkmcnt(0)
	s_barrier
	s_xor_b32 s0, s44, 1
	s_mul_i32 s0, s0, 0x5000
	s_cmp_ge_u32 s5, s26
	s_cbranch_scc1 .Lmla_w0_a
	s_waitcnt vmcnt(3)
	s_branch .Lmla_w1_a

.Lmla_w1_a:
	v_add3_u32 v246, s0, v211, v186
	ds_write_b128 v246, v[164:167] offset:51200
	v_add3_u32 v246, s0, v212, v186
	ds_write_b128 v246, v[160:163] offset:51200
	s_cmp_ge_u32 s5, s26
	s_cbranch_scc1 .Lmla_mid_done_a
	s_add_i32 s0, s25, s5
	s_add_i32 s1, s5, -4
	s_cmp_lt_u32 s45, 2
	s_cselect_b32 s0, s0, s1
	s_lshl_b32 s0, s0, 6
	s_add_i32 s0, s0, s24
	s_ashr_i32 s1, s0, 31
	s_lshl_b64 s[46:47], s[0:1], 11
	s_add_u32 s0, s6, s46
	s_addc_u32 s1, s7, s47
	v_lshl_add_u64 v[248:249], s[0:1], 0, v[192:193]
	v_lshl_add_u64 v[250:251], s[0:1], 0, v[194:195]
	v_lshl_add_u64 v[248:249], v[248:249], 0, v[180:181]
	v_lshl_add_u64 v[250:251], v[250:251], 0, v[180:181]
	global_load_dwordx4 v[164:167], v[248:249], off
	global_load_dwordx4 v[160:163], v[250:251], off

; template <int DQK, bool MOBA>
; __device__ __forceinline__ void attn_unit(const Args& A, int b, int h, int qb, lptr lds) {
;     ...
;         if (t + 1 < NT) { ATT_WRITE(buf ^ 1); if (t + 2 < NT) ATT_LOAD(t + 2); }
.LBB0_812:
	s_add_i32 s45, s5, -2
	s_and_b32 s44, s45, 1
	s_xor_b32 s0, s44, 1
	s_mul_i32 s1, s0, 0x6400
	v_add3_u32 v80, s1, v200, v186
	s_waitcnt vmcnt(2)
	ds_write_b128 v80, v[176:179]
	v_add3_u32 v80, s1, v201, v186
	ds_write_b128 v80, v[168:171]
	v_add3_u32 v80, s1, v210, v188
	ds_write_b128 v80, v[172:175] offset:256
	s_cmp_ge_u32 s5, s26
	s_cbranch_scc1 .LBB0_814
	s_add_i32 s0, s25, s5
	s_add_i32 s1, s5, -4
	s_cmp_lt_u32 s45, 2
	s_cselect_b32 s0, s0, s1
	s_lshl_b32 s0, s0, 6
	s_add_i32 s0, s0, s24
	s_ashr_i32 s1, s0, 31
	s_lshl_b64 s[46:47], s[0:1], 11
	s_add_u32 s48, s4, s46
	s_addc_u32 s49, s15, s47
	v_lshl_add_u64 v[80:81], s[48:49], 0, v[192:193]
	v_lshl_add_u64 v[80:81], v[80:81], 0, v[180:181]
	v_lshl_add_u64 v[82:83], s[48:49], 0, v[194:195]
	v_lshl_add_u64 v[82:83], v[82:83], 0, v[180:181]
	global_load_dwordx4 v[176:179], v[80:81], off
	global_load_dwordx4 v[168:171], v[82:83], off
	v_add_u32_e32 v80, s0, v199
	v_ashrrev_i32_e32 v81, 31, v80
	v_lshlrev_b64 v[80:81], 7, v[80:81]
	v_lshl_add_u64 v[80:81], v[190:191], 0, v[80:81]
	global_load_dwordx4 v[172:175], v[80:81], off

; template <int DQK, bool MOBA>
; __device__ __forceinline__ void attn_unit(const Args& A, int b, int h, int qb, lptr lds) {
;     ...
;         const int tt = t & 3; const bool diag = t < 4; const int blk = diag ? own : ((t - 4) >> 2);
;         const bool lsel = diag || ((sel >> blk) & 1u);
;         bool act;
;         if (diag) act = (64 * tt < 32 * (wid + 1));
;         else act = MOBA ? (__ballot(lsel) != 0ull) : true;
;         if (act) {
;             lptr kb = lds + L::OFF_K + buf * L::KBUF + r32 * L::KROW + 16 * hi;
;             f32x16 s0, s1;
; #pragma unroll
;             for (int r = 0; r < 16; ++r) { s0[r] = negm; s1[r] = negm; }
;             {
;                 bf16x8 ka[2][2], kc[2][2];
; #pragma unroll
;                 for (int i = 0; i < 2; ++i) { ka[0][i] = *(const LAS bf16x8*)(kb + 32 * i); kc[0][i] = *(const LAS bf16x8*)(kb + 32 * L::KROW + 32 * i); }
;                 __builtin_amdgcn_sched_barrier(0);
; #pragma unroll
;                 for (int sb = 0; sb < NS; sb += 2) {
;                     const int cur = (sb >> 1) & 1, nxt = cur ^ 1;
;                     if (sb + 2 < NS) {
; #pragma unroll
;                         for (int i = 0; i < 2; ++i) { ka[nxt][i] = *(const LAS bf16x8*)(kb + 32 * (sb + 2 + i)); kc[nxt][i] = *(const LAS bf16x8*)(kb + 32 * L::KROW + 32 * (sb + 2 + i)); }
;                     }
;                     __builtin_amdgcn_sched_barrier(0);
; #pragma unroll
;                     for (int i = 0; i < 2; ++i) { s0 = MFMA32(ka[cur][i], qf[sb + i], s0); s1 = MFMA32(kc[cur][i], qf[sb + i], s1); }
;                     __builtin_amdgcn_sched_barrier(0);
;                 }
;             }
;             if (MOBA) {
;                 const LAS int* pp = (const LAS int*)(lds + L::OFF_POS + buf * 256);
; #pragma unroll
;                 for (int a = 0; a < 4; ++a) {
;                     const i32x4 p0 = *(const LAS i32x4*)(pp + 8 * a + 4 * hi), p1 = *(const LAS i32x4*)(pp + 32 + 8 * a + 4 * hi);
;                     const int pa[4] = {p0.x, p0.y, p0.z, p0.w}, pb[4] = {p1.x, p1.y, p1.z, p1.w};
; #pragma unroll
;                     for (int e = 0; e < 4; ++e) {
;                         int d0 = pq - pa[e]; d0 = d0 < 0 ? 0 : (d0 > 1023 ? 1023 : d0);
;                         int d1 = pq - pb[e]; d1 = d1 < 0 ? 0 : (d1 > 1023 ? 1023 : d1);
;                         s0[4 * a + e] += lut[d0]; s1[4 * a + e] += lut[d1];
.Lmla_mid_done_b:
	s_branch .LBB0_811
.LBB0_817:
	s_add_i32 s4, s5, -2
	s_cmp_eq_u32 s22, 0
	s_cselect_b64 s[0:1], -1, 0
	s_cmp_lg_u32 s22, 0
	s_cselect_b64 s[6:7], -1, 0
	s_lshl_b32 s5, s4, 6
	s_cmp_le_i32 s5, s23
	s_cselect_b64 s[22:23], -1, 0
	s_or_b64 s[6:7], s[6:7], s[22:23]
	s_andn2_b64 vcc, exec, s[6:7]
	s_cbranch_vccnz .Lmla_skip_last
	s_and_b32 s4, s4, 1
	s_mul_i32 s6, s4, 0x6400
	s_waitcnt vmcnt(4)
	v_add_u32_e32 v176, s6, v213
	ds_read_b128 v[96:99], v176
	ds_read_b128 v[100:103], v176 offset:32
	ds_read_b128 v[104:107], v176 offset:12800
	ds_read_b128 v[108:111], v176 offset:12832
	s_waitcnt vmcnt(0)
	ds_read_b128 v[160:163], v176 offset:64
	ds_read_b128 v[164:167], v176 offset:96
	ds_read_b128 v[168:171], v176 offset:12864
	ds_read_b128 v[172:175], v176 offset:12896
	s_waitcnt lgkmcnt(7)
	v_mfma_f32_32x32x16_bf16 v[80:95], v[96:99], v[112:115], v[64:79]
	s_waitcnt lgkmcnt(5)
	v_mfma_f32_32x32x16_bf16 v[64:79], v[104:107], v[112:115], v[64:79]
	v_mfma_f32_32x32x16_bf16 v[80:95], v[100:103], v[116:119], v[80:95]
	s_waitcnt lgkmcnt(4)
	v_mfma_f32_32x32x16_bf16 v[64:79], v[108:111], v[116:119], v[64:79]
	ds_read_b128 v[96:99], v176 offset:128
	ds_read_b128 v[100:103], v176 offset:160
	ds_read_b128 v[104:107], v176 offset:12928
	ds_read_b128 v[108:111], v176 offset:12960
	s_waitcnt lgkmcnt(7)
	v_mfma_f32_32x32x16_bf16 v[80:95], v[160:163], v[120:123], v[80:95]
	s_waitcnt lgkmcnt(5)
	v_mfma_f32_32x32x16_bf16 v[64:79], v[168:171], v[120:123], v[64:79]
	v_mfma_f32_32x32x16_bf16 v[80:95], v[164:167], v[124:127], v[80:95]
	s_waitcnt lgkmcnt(4)
	v_mfma_f32_32x32x16_bf16 v[64:79], v[172:175], v[124:127], v[64:79]
	ds_read_b128 v[112:115], v176 offset:192
	ds_read_b128 v[116:119], v176 offset:224
	ds_read_b128 v[120:123], v176 offset:12992
	ds_read_b128 v[124:127], v176 offset:13024
	s_waitcnt lgkmcnt(7)
	v_mfma_f32_32x32x16_bf16 v[80:95], v[96:99], v[128:131], v[80:95]
	s_waitcnt lgkmcnt(5)
	v_mfma_f32_32x32x16_bf16 v[64:79], v[104:107], v[128:131], v[64:79]
	v_mfma_f32_32x32x16_bf16 v[80:95], v[100:103], v[132:135], v[80:95]
	s_waitcnt lgkmcnt(4)
	v_mfma_f32_32x32x16_bf16 v[64:79], v[108:111], v[132:135], v[64:79]
	ds_read_b128 v[96:99], v176 offset:256
	ds_read_b128 v[100:103], v176 offset:288
	ds_read_b128 v[104:107], v176 offset:13056
	ds_read_b128 v[108:111], v176 offset:13088
	s_waitcnt lgkmcnt(7)
	v_mfma_f32_32x32x16_bf16 v[80:95], v[112:115], v[136:139], v[80:95]
	s_waitcnt lgkmcnt(5)
	v_mfma_f32_32x32x16_bf16 v[64:79], v[120:123], v[136:139], v[64:79]
	v_mfma_f32_32x32x16_bf16 v[80:95], v[116:119], v[140:143], v[80:95]
	s_waitcnt lgkmcnt(4)
	v_mfma_f32_32x32x16_bf16 v[64:79], v[124:127], v[140:143], v[64:79]
	ds_read_b128 v[112:115], v176 offset:320
	ds_read_b128 v[116:119], v176 offset:352
	ds_read_b128 v[120:123], v176 offset:13120
	ds_read_b128 v[124:127], v176 offset:13152
	s_waitcnt lgkmcnt(7)
	v_mfma_f32_32x32x16_bf16 v[80:95], v[96:99], v[148:151], v[80:95]
	s_waitcnt lgkmcnt(5)
	v_mfma_f32_32x32x16_bf16 v[64:79], v[104:107], v[148:151], v[64:79]
	v_mfma_f32_32x32x16_bf16 v[80:95], v[100:103], v[156:159], v[80:95]
	s_waitcnt lgkmcnt(4)
	v_mfma_f32_32x32x16_bf16 v[64:79], v[108:111], v[156:159], v[64:79]
	s_waitcnt lgkmcnt(3)
	v_mfma_f32_32x32x16_bf16 v[80:95], v[112:115], v[144:147], v[80:95]
	s_waitcnt lgkmcnt(1)
	v_mfma_f32_32x32x16_bf16 v[64:79], v[120:123], v[144:147], v[64:79]
	v_mfma_f32_32x32x16_bf16 v[80:95], v[116:119], v[152:155], v[80:95]
	s_waitcnt lgkmcnt(0)
	v_mfma_f32_32x32x16_bf16 v[64:79], v[124:127], v[152:155], v[64:79]
	s_andn2_b64 vcc, exec, s[0:1]
	s_cbranch_vccnz .LBB0_802
	v_or_b32_e32 v96, s5, v183
	v_or_b32_e32 v97, 32, v96
	v_cmp_le_i32_e32 vcc, v97, v197
	v_or_b32_e32 v97, 33, v96
	s_nop 5
	v_cndmask_b32_e32 v64, v209, v64, vcc
	v_cmp_lt_i32_e32 vcc, v96, v197
	s_nop 1
	v_cndmask_b32_e32 v81, v209, v81, vcc
	v_cmp_le_i32_e32 vcc, v96, v197
	s_nop 1
	v_cndmask_b32_e32 v80, v209, v80, vcc
	v_cmp_le_i32_e32 vcc, v97, v197
	v_or_b32_e32 v97, 2, v96
	s_nop 0
	v_cndmask_b32_e32 v65, v209, v65, vcc
	v_cmp_le_i32_e32 vcc, v97, v197
	v_or_b32_e32 v97, 34, v96
	s_nop 0
	v_cndmask_b32_e32 v82, v209, v82, vcc
	v_cmp_le_i32_e32 vcc, v97, v197
	v_or_b32_e32 v97, 3, v96
	s_nop 0
	v_cndmask_b32_e32 v66, v209, v66, vcc
	v_cmp_le_i32_e32 vcc, v97, v197
	v_or_b32_e32 v97, 35, v96
	s_nop 0
	v_cndmask_b32_e32 v83, v209, v83, vcc
	v_cmp_le_i32_e32 vcc, v97, v197
	v_or_b32_e32 v97, 8, v96
	s_nop 0
	v_cndmask_b32_e32 v67, v209, v67, vcc
	v_cmp_le_i32_e32 vcc, v97, v197
	v_or_b32_e32 v97, 40, v96
	s_nop 0
	v_cndmask_b32_e32 v84, v209, v84, vcc
	v_cmp_le_i32_e32 vcc, v97, v197
	v_or_b32_e32 v97, 9, v96
	s_nop 0
	v_cndmask_b32_e32 v68, v209, v68, vcc
	v_cmp_le_i32_e32 vcc, v97, v197
	v_or_b32_e32 v97, 41, v96
	s_nop 0
	v_cndmask_b32_e32 v85, v209, v85, vcc
	v_cmp_le_i32_e32 vcc, v97, v197
	v_or_b32_e32 v97, 10, v96
	s_nop 0
	v_cndmask_b32_e32 v69, v209, v69, vcc
	v_cmp_le_i32_e32 vcc, v97, v197
	v_or_b32_e32 v97, 42, v96
	s_nop 0
	v_cndmask_b32_e32 v86, v209, v86, vcc
	v_cmp_le_i32_e32 vcc, v97, v197
	v_or_b32_e32 v97, 11, v96
	s_nop 0
	v_cndmask_b32_e32 v70, v209, v70, vcc
	v_cmp_le_i32_e32 vcc, v97, v197
	v_or_b32_e32 v97, 43, v96
	s_nop 0
	v_cndmask_b32_e32 v87, v209, v87, vcc
	v_cmp_le_i32_e32 vcc, v97, v197
	v_or_b32_e32 v97, 16, v96
	s_nop 0
	v_cndmask_b32_e32 v71, v209, v71, vcc
	v_cmp_le_i32_e32 vcc, v97, v197
	v_or_b32_e32 v97, 48, v96
	s_nop 0
	v_cndmask_b32_e32 v88, v209, v88, vcc
	v_cmp_le_i32_e32 vcc, v97, v197
	v_or_b32_e32 v97, 17, v96
	s_nop 0
	v_cndmask_b32_e32 v72, v209, v72, vcc
	v_cmp_le_i32_e32 vcc, v97, v197
	v_or_b32_e32 v97, 49, v96
	s_nop 0
	v_cndmask_b32_e32 v89, v209, v89, vcc
	v_cmp_le_i32_e32 vcc, v97, v197
	v_or_b32_e32 v97, 18, v96
	s_nop 0
	v_cndmask_b32_e32 v73, v209, v73, vcc
	v_cmp_le_i32_e32 vcc, v97, v197
	v_or_b32_e32 v97, 50, v96
	s_nop 0
	v_cndmask_b32_e32 v90, v209, v90, vcc
	v_cmp_le_i32_e32 vcc, v97, v197
	v_or_b32_e32 v97, 19, v96
	s_nop 0
	v_cndmask_b32_e32 v74, v209, v74, vcc
	v_cmp_le_i32_e32 vcc, v97, v197
	v_or_b32_e32 v97, 51, v96
	s_nop 0
	v_cndmask_b32_e32 v91, v209, v91, vcc
	v_cmp_le_i32_e32 vcc, v97, v197
	v_or_b32_e32 v97, 24, v96
	s_nop 0
	v_cndmask_b32_e32 v75, v209, v75, vcc
	v_cmp_le_i32_e32 vcc, v97, v197
	v_or_b32_e32 v97, 56, v96
	s_nop 0
	v_cndmask_b32_e32 v92, v209, v92, vcc
	v_cmp_le_i32_e32 vcc, v97, v197
	v_or_b32_e32 v97, 25, v96
	s_nop 0
	v_cndmask_b32_e32 v76, v209, v76, vcc
	v_cmp_le_i32_e32 vcc, v97, v197
	v_or_b32_e32 v97, 57, v96
	s_nop 0
	v_cndmask_b32_e32 v93, v209, v93, vcc
	v_cmp_le_i32_e32 vcc, v97, v197
	v_or_b32_e32 v97, 26, v96
	s_nop 0
	v_cndmask_b32_e32 v77, v209, v77, vcc
	v_cmp_le_i32_e32 vcc, v97, v197
	v_or_b32_e32 v97, 58, v96
	s_nop 0
	v_cndmask_b32_e32 v94, v209, v94, vcc
	v_cmp_le_i32_e32 vcc, v97, v197
	v_or_b32_e32 v97, 27, v96
	v_or_b32_e32 v96, 59, v96
	v_cndmask_b32_e32 v78, v209, v78, vcc
	v_cmp_le_i32_e32 vcc, v97, v197
	s_nop 1
	v_cndmask_b32_e32 v95, v209, v95, vcc
	v_cmp_le_i32_e32 vcc, v96, v197
	s_nop 1
	v_cndmask_b32_e32 v79, v209, v79, vcc
	s_branch .LBB0_802
; template <int DQK, bool MOBA>
; __device__ __forceinline__ void attn_unit(const Args& A, int b, int h, int qb, lptr lds) {
;     ...
;         bool act;
;         if (diag) act = (64 * tt < 32 * (wid + 1));
;         else act = MOBA ? (__ballot(lsel) != 0ull) : true;
;         if (act) {
;     ...
;         __syncthreads();
.Lmla_skip_last:
	s_waitcnt lgkmcnt(0)
	s_barrier
	s_branch .LBB0_803
